# conv: row prefetch depth 3 instead of 4 (depth 8 was slower: probing the other side)
# speedup vs baseline: 1.0075x; 1.0042x over previous
; __device__ __forceinline__ unsigned cvt_pk_bf16(float lo, float hi) { unsigned r; asm volatile("v_cvt_pk_bf16_f32 %0, %1, %2" : "=v"(r) : "v"(lo), "v"(hi)); return r; }
; __device__ __forceinline__ float bf_lo(unsigned w) { return __uint_as_float(w << 16); }
; __device__ __forceinline__ float bf_hi(unsigned w) { return __uint_as_float(w & 0xffff0000u); }
; __global__ void __launch_bounds__(512, 2) trunk_fwd(Args args) {
;     ...
;                 u32x4 gb_n = *(const u32x4*)(Z + (size_t)r0 * INP + 768 + c0), gu_n = *(const u32x4*)(Z + (size_t)r0 * INP + 1280 + c0);
;                 f32x4 pv_n = *(const f32x4*)(pl + (size_t)r0 * PLE + lane * 4);
; #pragma nounroll
;                 for (int rr = 0; rr < 16; ++rr) {
;                     const int r = r0 + rr;
;                     const u32x4 gb = gb_n, gu = gu_n; const f32x4 pv4 = pv_n;
;                     if (rr < 15) { gb_n = *(const u32x4*)(Z + (size_t)(r + 1) * INP + 768 + c0); gu_n = *(const u32x4*)(Z + (size_t)(r + 1) * INP + 1280 + c0);
;                                    pv_n = *(const f32x4*)(pl + (size_t)(r + 1) * PLE + lane * 4); }
;                     float cv[8], uu[8]; float ss = 0.f;
; #pragma unroll
;                     for (int i = 0; i < 4; ++i) {
;                         uu[2 * i] = bf_lo(gu[i]); uu[2 * i + 1] = bf_hi(gu[i]);
;                         cv[2 * i] = bf_lo(gb[i]) * (w0[2 * i] * uu[2 * i] + w1[2 * i] * u1[2 * i] + w2[2 * i] * u2[2 * i]);
;                         cv[2 * i + 1] = bf_hi(gb[i]) * (w0[2 * i + 1] * uu[2 * i + 1] + w1[2 * i + 1] * u1[2 * i + 1] + w2[2 * i + 1] * u2[2 * i + 1]);
;                     }
; #pragma unroll
;                     for (int i = 0; i < 8; ++i) { ss += cv[i] * cv[i]; u2[i] = u1[i]; u1[i] = uu[i]; }
;                     ss = wave_sum(ss);
;                     const float rc = rsqrtf(ss * (1.0f / 512.0f) + EPS);
;                     u32x4 oc;
; #pragma unroll
;                     for (int i = 0; i < 4; ++i) oc[i] = cvt_pk_bf16(cv[2 * i] * rc, cv[2 * i + 1] * rc);
;                     *(u32x4*)(MIX + (size_t)r * 1024 + 512 + c0) = oc;
.Lcv_taps_ok:
	v_mad_i64_i32 v[152:153], vcc, s41, v221, v[58:59]
	s_add_u32 s41, s41, 1
	global_load_dwordx4 v[2:5], v[152:153], off offset:1536
	global_load_dwordx4 v[18:21], v[152:153], off offset:2560
	v_mad_i64_i32 v[152:153], vcc, s41, v221, v[58:59]
	s_add_u32 s41, s41, 1
	global_load_dwordx4 v[6:9], v[152:153], off offset:1536
	global_load_dwordx4 v[22:25], v[152:153], off offset:2560
	v_mad_i64_i32 v[152:153], vcc, s41, v221, v[58:59]
	s_add_u32 s41, s41, 1
	global_load_dwordx4 v[10:13], v[152:153], off offset:1536
	global_load_dwordx4 v[26:29], v[152:153], off offset:2560
	s_waitcnt vmcnt(4)
	v_lshlrev_b32_e32 v188, 16, v18
	v_and_b32_e32 v189, 0xffff0000, v18
	v_lshlrev_b32_e32 v190, 16, v19
	v_and_b32_e32 v191, 0xffff0000, v19
	v_lshlrev_b32_e32 v192, 16, v20
	v_and_b32_e32 v193, 0xffff0000, v20
	v_lshlrev_b32_e32 v194, 16, v21
	v_and_b32_e32 v195, 0xffff0000, v21
	v_mul_f32_e32 v140, v164, v188
	v_mul_f32_e32 v141, v165, v189
	v_mul_f32_e32 v142, v166, v190
	v_mul_f32_e32 v143, v167, v191
	v_mul_f32_e32 v144, v168, v192
	v_mul_f32_e32 v145, v169, v193
	v_mul_f32_e32 v146, v170, v194
	v_mul_f32_e32 v147, v171, v195
	v_fmac_f32_e32 v140, v172, v204
	v_fmac_f32_e32 v141, v173, v205
	v_fmac_f32_e32 v142, v174, v206
	v_fmac_f32_e32 v143, v175, v207
	v_fmac_f32_e32 v144, v176, v208
	v_fmac_f32_e32 v145, v177, v209
	v_fmac_f32_e32 v146, v178, v210
	v_fmac_f32_e32 v147, v179, v211
	v_fmac_f32_e32 v140, v180, v196
	v_fmac_f32_e32 v141, v181, v197
	v_fmac_f32_e32 v142, v182, v198
	v_fmac_f32_e32 v143, v183, v199
	v_fmac_f32_e32 v144, v184, v200
	v_fmac_f32_e32 v145, v185, v201
	v_fmac_f32_e32 v146, v186, v202
	v_fmac_f32_e32 v147, v187, v203
	v_lshlrev_b32_e32 v150, 16, v2
	v_and_b32_e32 v151, 0xffff0000, v2
	v_mul_f32_e32 v140, v150, v140
	v_mul_f32_e32 v141, v151, v141
	v_lshlrev_b32_e32 v150, 16, v3
	v_and_b32_e32 v151, 0xffff0000, v3
	v_mul_f32_e32 v142, v150, v142
	v_mul_f32_e32 v143, v151, v143
	v_lshlrev_b32_e32 v150, 16, v4
	v_and_b32_e32 v151, 0xffff0000, v4
	v_mul_f32_e32 v144, v150, v144
	v_mul_f32_e32 v145, v151, v145
	v_lshlrev_b32_e32 v150, 16, v5
	v_and_b32_e32 v151, 0xffff0000, v5
	v_mul_f32_e32 v146, v150, v146
	v_mul_f32_e32 v147, v151, v147
	v_mul_f32_e32 v148, v140, v140
	v_fmac_f32_e32 v148, v141, v141
	v_fmac_f32_e32 v148, v142, v142
	v_fmac_f32_e32 v148, v143, v143
	v_fmac_f32_e32 v148, v144, v144
	v_fmac_f32_e32 v148, v145, v145
	v_fmac_f32_e32 v148, v146, v146
	v_fmac_f32_e32 v148, v147, v147
	v_mad_i64_i32 v[152:153], vcc, s41, v221, v[58:59]
	s_add_u32 s41, s41, 1
	global_load_dwordx4 v[2:5], v[152:153], off offset:1536
	global_load_dwordx4 v[18:21], v[152:153], off offset:2560
	s_nop 1
	v_add_f32_dpp v148, v148, v148 quad_perm:[1,0,3,2] row_mask:0xf bank_mask:0xf
	s_nop 1
	v_add_f32_dpp v148, v148, v148 quad_perm:[2,3,0,1] row_mask:0xf bank_mask:0xf
	s_nop 1
	v_add_f32_dpp v148, v148, v148 row_half_mirror row_mask:0xf bank_mask:0xf
	s_nop 1
	v_add_f32_dpp v148, v148, v148 row_mirror row_mask:0xf bank_mask:0xf
	s_nop 1
	v_add_f32_dpp v148, v148, v148 row_bcast:15 row_mask:0xa bank_mask:0xf
	s_nop 1
	v_add_f32_dpp v148, v148, v148 row_bcast:31 row_mask:0xc bank_mask:0xf
	s_nop 0
	v_readlane_b32 s0, v148, 63
	s_nop 1
	v_mov_b32_e32 v148, s0
	v_fmamk_f32 v148, v148, 0x3b000000, v162
	v_mul_f32_e32 v150, 0x4b800000, v148
	v_cmp_gt_f32_e32 vcc, s31, v148
	s_nop 1
	v_cndmask_b32_e32 v148, v148, v150, vcc
	v_rsq_f32_e32 v148, v148
	s_nop 0
	v_mul_f32_e32 v150, 0x45800000, v148
	v_cndmask_b32_e32 v149, v148, v150, vcc
	v_mul_f32_e32 v140, v149, v140
	v_mul_f32_e32 v141, v149, v141
	v_mul_f32_e32 v142, v149, v142
	v_mul_f32_e32 v143, v149, v143
	v_mul_f32_e32 v144, v149, v144
	v_mul_f32_e32 v145, v149, v145
	v_mul_f32_e32 v146, v149, v146
	v_mul_f32_e32 v147, v149, v147
	v_cvt_pk_bf16_f32 v140, v140, v141
	v_cvt_pk_bf16_f32 v141, v142, v143
	v_cvt_pk_bf16_f32 v142, v144, v145
	v_cvt_pk_bf16_f32 v143, v146, v147
	global_store_dwordx4 v[156:157], v[140:143], off sc1
	s_waitcnt vmcnt(5)
	v_lshlrev_b32_e32 v196, 16, v22
	v_and_b32_e32 v197, 0xffff0000, v22
	v_lshlrev_b32_e32 v198, 16, v23
	v_and_b32_e32 v199, 0xffff0000, v23
	v_lshlrev_b32_e32 v200, 16, v24
	v_and_b32_e32 v201, 0xffff0000, v24
	v_lshlrev_b32_e32 v202, 16, v25
	v_and_b32_e32 v203, 0xffff0000, v25
	v_mul_f32_e32 v140, v164, v196
	v_mul_f32_e32 v141, v165, v197
	v_mul_f32_e32 v142, v166, v198
	v_mul_f32_e32 v143, v167, v199
	v_mul_f32_e32 v144, v168, v200
	v_mul_f32_e32 v145, v169, v201
	v_mul_f32_e32 v146, v170, v202
	v_mul_f32_e32 v147, v171, v203
	v_fmac_f32_e32 v140, v172, v188
	v_fmac_f32_e32 v141, v173, v189
	v_fmac_f32_e32 v142, v174, v190
	v_fmac_f32_e32 v143, v175, v191
	v_fmac_f32_e32 v144, v176, v192
	v_fmac_f32_e32 v145, v177, v193
	v_fmac_f32_e32 v146, v178, v194
	v_fmac_f32_e32 v147, v179, v195
	v_fmac_f32_e32 v140, v180, v204
	v_fmac_f32_e32 v141, v181, v205
	v_fmac_f32_e32 v142, v182, v206
	v_fmac_f32_e32 v143, v183, v207
	v_fmac_f32_e32 v144, v184, v208
	v_fmac_f32_e32 v145, v185, v209
	v_fmac_f32_e32 v146, v186, v210
	v_fmac_f32_e32 v147, v187, v211
	v_lshlrev_b32_e32 v150, 16, v6
	v_and_b32_e32 v151, 0xffff0000, v6
	v_mul_f32_e32 v140, v150, v140
	v_mul_f32_e32 v141, v151, v141
	v_lshlrev_b32_e32 v150, 16, v7
	v_and_b32_e32 v151, 0xffff0000, v7
	v_mul_f32_e32 v142, v150, v142
	v_mul_f32_e32 v143, v151, v143
	v_lshlrev_b32_e32 v150, 16, v8
	v_and_b32_e32 v151, 0xffff0000, v8
	v_mul_f32_e32 v144, v150, v144
	v_mul_f32_e32 v145, v151, v145
	v_lshlrev_b32_e32 v150, 16, v9
	v_and_b32_e32 v151, 0xffff0000, v9
	v_mul_f32_e32 v146, v150, v146
	v_mul_f32_e32 v147, v151, v147
	v_mul_f32_e32 v148, v140, v140
	v_fmac_f32_e32 v148, v141, v141
; __device__ __forceinline__ unsigned cvt_pk_bf16(float lo, float hi) { unsigned r; asm volatile("v_cvt_pk_bf16_f32 %0, %1, %2" : "=v"(r) : "v"(lo), "v"(hi)); return r; }
; __device__ __forceinline__ float bf_lo(unsigned w) { return __uint_as_float(w << 16); }
; __device__ __forceinline__ float bf_hi(unsigned w) { return __uint_as_float(w & 0xffff0000u); }
; __global__ void __launch_bounds__(512, 2) trunk_fwd(Args args) {
;     ...
;                 for (int rr = 0; rr < 16; ++rr) {
;                     const int r = r0 + rr;
;                     const u32x4 gb = gb_n, gu = gu_n; const f32x4 pv4 = pv_n;
;                     if (rr < 15) { gb_n = *(const u32x4*)(Z + (size_t)(r + 1) * INP + 768 + c0); gu_n = *(const u32x4*)(Z + (size_t)(r + 1) * INP + 1280 + c0);
;                                    pv_n = *(const f32x4*)(pl + (size_t)(r + 1) * PLE + lane * 4); }
;                     float cv[8], uu[8]; float ss = 0.f;
; #pragma unroll
;                     for (int i = 0; i < 4; ++i) {
;                         uu[2 * i] = bf_lo(gu[i]); uu[2 * i + 1] = bf_hi(gu[i]);
;                         cv[2 * i] = bf_lo(gb[i]) * (w0[2 * i] * uu[2 * i] + w1[2 * i] * u1[2 * i] + w2[2 * i] * u2[2 * i]);
;                         cv[2 * i + 1] = bf_hi(gb[i]) * (w0[2 * i + 1] * uu[2 * i + 1] + w1[2 * i + 1] * u1[2 * i + 1] + w2[2 * i + 1] * u2[2 * i + 1]);
;                     }
; #pragma unroll
;                     for (int i = 0; i < 8; ++i) { ss += cv[i] * cv[i]; u2[i] = u1[i]; u1[i] = uu[i]; }
;                     ss = wave_sum(ss);
;                     const float rc = rsqrtf(ss * (1.0f / 512.0f) + EPS);
;                     u32x4 oc;
; #pragma unroll
;                     for (int i = 0; i < 4; ++i) oc[i] = cvt_pk_bf16(cv[2 * i] * rc, cv[2 * i + 1] * rc);
;                     *(u32x4*)(MIX + (size_t)r * 1024 + 512 + c0) = oc;
	v_fmac_f32_e32 v148, v142, v142
	v_fmac_f32_e32 v148, v143, v143
	v_fmac_f32_e32 v148, v144, v144
	v_fmac_f32_e32 v148, v145, v145
	v_fmac_f32_e32 v148, v146, v146
	v_fmac_f32_e32 v148, v147, v147
	v_mad_i64_i32 v[152:153], vcc, s41, v221, v[58:59]
	s_add_u32 s41, s41, 1
	global_load_dwordx4 v[6:9], v[152:153], off offset:1536
	global_load_dwordx4 v[22:25], v[152:153], off offset:2560
	s_nop 1
	v_add_f32_dpp v148, v148, v148 quad_perm:[1,0,3,2] row_mask:0xf bank_mask:0xf
	s_nop 1
	v_add_f32_dpp v148, v148, v148 quad_perm:[2,3,0,1] row_mask:0xf bank_mask:0xf
	s_nop 1
	v_add_f32_dpp v148, v148, v148 row_half_mirror row_mask:0xf bank_mask:0xf
	s_nop 1
	v_add_f32_dpp v148, v148, v148 row_mirror row_mask:0xf bank_mask:0xf
	s_nop 1
	v_add_f32_dpp v148, v148, v148 row_bcast:15 row_mask:0xa bank_mask:0xf
	s_nop 1
	v_add_f32_dpp v148, v148, v148 row_bcast:31 row_mask:0xc bank_mask:0xf
	s_nop 0
	v_readlane_b32 s0, v148, 63
	s_nop 1
	v_mov_b32_e32 v148, s0
	v_fmamk_f32 v148, v148, 0x3b000000, v162
	v_mul_f32_e32 v150, 0x4b800000, v148
	v_cmp_gt_f32_e32 vcc, s31, v148
	s_nop 1
	v_cndmask_b32_e32 v148, v148, v150, vcc
	v_rsq_f32_e32 v148, v148
	s_nop 0
	v_mul_f32_e32 v150, 0x45800000, v148
	v_cndmask_b32_e32 v149, v148, v150, vcc
	v_mul_f32_e32 v140, v149, v140
	v_mul_f32_e32 v141, v149, v141
	v_mul_f32_e32 v142, v149, v142
	v_mul_f32_e32 v143, v149, v143
	v_mul_f32_e32 v144, v149, v144
	v_mul_f32_e32 v145, v149, v145
	v_mul_f32_e32 v146, v149, v146
	v_mul_f32_e32 v147, v149, v147
	v_cvt_pk_bf16_f32 v140, v140, v141
	v_cvt_pk_bf16_f32 v141, v142, v143
	v_cvt_pk_bf16_f32 v142, v144, v145
	v_cvt_pk_bf16_f32 v143, v146, v147
	global_store_dwordx4 v[156:157], v[140:143], off offset:2048 sc1
	v_lshl_add_u64 v[156:157], v[156:157], 0, s[20:21]
	s_waitcnt vmcnt(6)
	v_lshlrev_b32_e32 v204, 16, v26
	v_and_b32_e32 v205, 0xffff0000, v26
	v_lshlrev_b32_e32 v206, 16, v27
	v_and_b32_e32 v207, 0xffff0000, v27
	v_lshlrev_b32_e32 v208, 16, v28
	v_and_b32_e32 v209, 0xffff0000, v28
	v_lshlrev_b32_e32 v210, 16, v29
	v_and_b32_e32 v211, 0xffff0000, v29
	v_mul_f32_e32 v140, v164, v204
	v_mul_f32_e32 v141, v165, v205
	v_mul_f32_e32 v142, v166, v206
	v_mul_f32_e32 v143, v167, v207
	v_mul_f32_e32 v144, v168, v208
	v_mul_f32_e32 v145, v169, v209
	v_mul_f32_e32 v146, v170, v210
	v_mul_f32_e32 v147, v171, v211
	v_fmac_f32_e32 v140, v172, v196
	v_fmac_f32_e32 v141, v173, v197
	v_fmac_f32_e32 v142, v174, v198
	v_fmac_f32_e32 v143, v175, v199
	v_fmac_f32_e32 v144, v176, v200
	v_fmac_f32_e32 v145, v177, v201
	v_fmac_f32_e32 v146, v178, v202
	v_fmac_f32_e32 v147, v179, v203
	v_fmac_f32_e32 v140, v180, v188
	v_fmac_f32_e32 v141, v181, v189
	v_fmac_f32_e32 v142, v182, v190
	v_fmac_f32_e32 v143, v183, v191
	v_fmac_f32_e32 v144, v184, v192
	v_fmac_f32_e32 v145, v185, v193
	v_fmac_f32_e32 v146, v186, v194
	v_fmac_f32_e32 v147, v187, v195
	v_lshlrev_b32_e32 v150, 16, v10
	v_and_b32_e32 v151, 0xffff0000, v10
	v_mul_f32_e32 v140, v150, v140
	v_mul_f32_e32 v141, v151, v141
	v_lshlrev_b32_e32 v150, 16, v11
	v_and_b32_e32 v151, 0xffff0000, v11
	v_mul_f32_e32 v142, v150, v142
	v_mul_f32_e32 v143, v151, v143
	v_lshlrev_b32_e32 v150, 16, v12
	v_and_b32_e32 v151, 0xffff0000, v12
	v_mul_f32_e32 v144, v150, v144
	v_mul_f32_e32 v145, v151, v145
	v_lshlrev_b32_e32 v150, 16, v13
	v_and_b32_e32 v151, 0xffff0000, v13
	v_mul_f32_e32 v146, v150, v146
	v_mul_f32_e32 v147, v151, v147
	v_mul_f32_e32 v148, v140, v140
	v_fmac_f32_e32 v148, v141, v141
	v_fmac_f32_e32 v148, v142, v142
	v_fmac_f32_e32 v148, v143, v143
	v_fmac_f32_e32 v148, v144, v144
	v_fmac_f32_e32 v148, v145, v145
	v_fmac_f32_e32 v148, v146, v146
	v_fmac_f32_e32 v148, v147, v147
	v_mad_i64_i32 v[152:153], vcc, s41, v221, v[58:59]
	s_add_u32 s41, s41, 1
	global_load_dwordx4 v[10:13], v[152:153], off offset:1536
	global_load_dwordx4 v[26:29], v[152:153], off offset:2560
	s_nop 1
	v_add_f32_dpp v148, v148, v148 quad_perm:[1,0,3,2] row_mask:0xf bank_mask:0xf
	s_nop 1
	v_add_f32_dpp v148, v148, v148 quad_perm:[2,3,0,1] row_mask:0xf bank_mask:0xf
	s_nop 1
	v_add_f32_dpp v148, v148, v148 row_half_mirror row_mask:0xf bank_mask:0xf
	s_nop 1
	v_add_f32_dpp v148, v148, v148 row_mirror row_mask:0xf bank_mask:0xf
	s_nop 1
	v_add_f32_dpp v148, v148, v148 row_bcast:15 row_mask:0xa bank_mask:0xf
	s_nop 1
	v_add_f32_dpp v148, v148, v148 row_bcast:31 row_mask:0xc bank_mask:0xf
	s_nop 0
	v_readlane_b32 s0, v148, 63
	s_nop 1
	v_mov_b32_e32 v148, s0
	v_fmamk_f32 v148, v148, 0x3b000000, v162
	v_mul_f32_e32 v150, 0x4b800000, v148
	v_cmp_gt_f32_e32 vcc, s31, v148
	s_nop 1
	v_cndmask_b32_e32 v148, v148, v150, vcc
	v_rsq_f32_e32 v148, v148
	s_nop 0
	v_mul_f32_e32 v150, 0x45800000, v148
	v_cndmask_b32_e32 v149, v148, v150, vcc
	v_mul_f32_e32 v140, v149, v140
	v_mul_f32_e32 v141, v149, v141
	v_mul_f32_e32 v142, v149, v142
	v_mul_f32_e32 v143, v149, v143
	v_mul_f32_e32 v144, v149, v144
	v_mul_f32_e32 v145, v149, v145
	v_mul_f32_e32 v146, v149, v146
	v_mul_f32_e32 v147, v149, v147
	v_cvt_pk_bf16_f32 v140, v140, v141
	v_cvt_pk_bf16_f32 v141, v142, v143
	v_cvt_pk_bf16_f32 v142, v144, v145
	v_cvt_pk_bf16_f32 v143, v146, v147
	global_store_dwordx4 v[156:157], v[140:143], off sc1
	s_waitcnt vmcnt(7)
; __device__ __forceinline__ unsigned cvt_pk_bf16(float lo, float hi) { unsigned r; asm volatile("v_cvt_pk_bf16_f32 %0, %1, %2" : "=v"(r) : "v"(lo), "v"(hi)); return r; }
; __device__ __forceinline__ float bf_lo(unsigned w) { return __uint_as_float(w << 16); }
; __device__ __forceinline__ float bf_hi(unsigned w) { return __uint_as_float(w & 0xffff0000u); }
; __global__ void __launch_bounds__(512, 2) trunk_fwd(Args args) {
;     ...
;                 for (int rr = 0; rr < 16; ++rr) {
;                     const int r = r0 + rr;
;                     const u32x4 gb = gb_n, gu = gu_n; const f32x4 pv4 = pv_n;
;                     if (rr < 15) { gb_n = *(const u32x4*)(Z + (size_t)(r + 1) * INP + 768 + c0); gu_n = *(const u32x4*)(Z + (size_t)(r + 1) * INP + 1280 + c0);
;                                    pv_n = *(const f32x4*)(pl + (size_t)(r + 1) * PLE + lane * 4); }
;                     float cv[8], uu[8]; float ss = 0.f;
; #pragma unroll
;                     for (int i = 0; i < 4; ++i) {
;                         uu[2 * i] = bf_lo(gu[i]); uu[2 * i + 1] = bf_hi(gu[i]);
;                         cv[2 * i] = bf_lo(gb[i]) * (w0[2 * i] * uu[2 * i] + w1[2 * i] * u1[2 * i] + w2[2 * i] * u2[2 * i]);
;                         cv[2 * i + 1] = bf_hi(gb[i]) * (w0[2 * i + 1] * uu[2 * i + 1] + w1[2 * i + 1] * u1[2 * i + 1] + w2[2 * i + 1] * u2[2 * i + 1]);
;                     }
; #pragma unroll
;                     for (int i = 0; i < 8; ++i) { ss += cv[i] * cv[i]; u2[i] = u1[i]; u1[i] = uu[i]; }
;                     ss = wave_sum(ss);
;                     const float rc = rsqrtf(ss * (1.0f / 512.0f) + EPS);
;                     u32x4 oc;
; #pragma unroll
;                     for (int i = 0; i < 4; ++i) oc[i] = cvt_pk_bf16(cv[2 * i] * rc, cv[2 * i + 1] * rc);
;                     *(u32x4*)(MIX + (size_t)r * 1024 + 512 + c0) = oc;
	v_lshlrev_b32_e32 v188, 16, v18
	v_and_b32_e32 v189, 0xffff0000, v18
	v_lshlrev_b32_e32 v190, 16, v19
	v_and_b32_e32 v191, 0xffff0000, v19
	v_lshlrev_b32_e32 v192, 16, v20
	v_and_b32_e32 v193, 0xffff0000, v20
	v_lshlrev_b32_e32 v194, 16, v21
	v_and_b32_e32 v195, 0xffff0000, v21
	v_mul_f32_e32 v140, v164, v188
	v_mul_f32_e32 v141, v165, v189
	v_mul_f32_e32 v142, v166, v190
	v_mul_f32_e32 v143, v167, v191
	v_mul_f32_e32 v144, v168, v192
	v_mul_f32_e32 v145, v169, v193
	v_mul_f32_e32 v146, v170, v194
	v_mul_f32_e32 v147, v171, v195
	v_fmac_f32_e32 v140, v172, v204
	v_fmac_f32_e32 v141, v173, v205
	v_fmac_f32_e32 v142, v174, v206
	v_fmac_f32_e32 v143, v175, v207
	v_fmac_f32_e32 v144, v176, v208
	v_fmac_f32_e32 v145, v177, v209
	v_fmac_f32_e32 v146, v178, v210
	v_fmac_f32_e32 v147, v179, v211
	v_fmac_f32_e32 v140, v180, v196
	v_fmac_f32_e32 v141, v181, v197
	v_fmac_f32_e32 v142, v182, v198
	v_fmac_f32_e32 v143, v183, v199
	v_fmac_f32_e32 v144, v184, v200
	v_fmac_f32_e32 v145, v185, v201
	v_fmac_f32_e32 v146, v186, v202
	v_fmac_f32_e32 v147, v187, v203
	v_lshlrev_b32_e32 v150, 16, v2
	v_and_b32_e32 v151, 0xffff0000, v2
	v_mul_f32_e32 v140, v150, v140
	v_mul_f32_e32 v141, v151, v141
	v_lshlrev_b32_e32 v150, 16, v3
	v_and_b32_e32 v151, 0xffff0000, v3
	v_mul_f32_e32 v142, v150, v142
	v_mul_f32_e32 v143, v151, v143
	v_lshlrev_b32_e32 v150, 16, v4
	v_and_b32_e32 v151, 0xffff0000, v4
	v_mul_f32_e32 v144, v150, v144
	v_mul_f32_e32 v145, v151, v145
	v_lshlrev_b32_e32 v150, 16, v5
	v_and_b32_e32 v151, 0xffff0000, v5
	v_mul_f32_e32 v146, v150, v146
	v_mul_f32_e32 v147, v151, v147
	v_mul_f32_e32 v148, v140, v140
	v_fmac_f32_e32 v148, v141, v141
	v_fmac_f32_e32 v148, v142, v142
	v_fmac_f32_e32 v148, v143, v143
	v_fmac_f32_e32 v148, v144, v144
	v_fmac_f32_e32 v148, v145, v145
	v_fmac_f32_e32 v148, v146, v146
	v_fmac_f32_e32 v148, v147, v147
	v_mad_i64_i32 v[152:153], vcc, s41, v221, v[58:59]
	s_add_u32 s41, s41, 1
	global_load_dwordx4 v[2:5], v[152:153], off offset:1536
	global_load_dwordx4 v[18:21], v[152:153], off offset:2560
	s_nop 1
	v_add_f32_dpp v148, v148, v148 quad_perm:[1,0,3,2] row_mask:0xf bank_mask:0xf
	s_nop 1
	v_add_f32_dpp v148, v148, v148 quad_perm:[2,3,0,1] row_mask:0xf bank_mask:0xf
	s_nop 1
	v_add_f32_dpp v148, v148, v148 row_half_mirror row_mask:0xf bank_mask:0xf
	s_nop 1
	v_add_f32_dpp v148, v148, v148 row_mirror row_mask:0xf bank_mask:0xf
	s_nop 1
	v_add_f32_dpp v148, v148, v148 row_bcast:15 row_mask:0xa bank_mask:0xf
	s_nop 1
	v_add_f32_dpp v148, v148, v148 row_bcast:31 row_mask:0xc bank_mask:0xf
	s_nop 0
	v_readlane_b32 s0, v148, 63
	s_nop 1
	v_mov_b32_e32 v148, s0
	v_fmamk_f32 v148, v148, 0x3b000000, v162
	v_mul_f32_e32 v150, 0x4b800000, v148
	v_cmp_gt_f32_e32 vcc, s31, v148
	s_nop 1
	v_cndmask_b32_e32 v148, v148, v150, vcc
	v_rsq_f32_e32 v148, v148
	s_nop 0
	v_mul_f32_e32 v150, 0x45800000, v148
	v_cndmask_b32_e32 v149, v148, v150, vcc
	v_mul_f32_e32 v140, v149, v140
	v_mul_f32_e32 v141, v149, v141
	v_mul_f32_e32 v142, v149, v142
	v_mul_f32_e32 v143, v149, v143
	v_mul_f32_e32 v144, v149, v144
	v_mul_f32_e32 v145, v149, v145
	v_mul_f32_e32 v146, v149, v146
	v_mul_f32_e32 v147, v149, v147
	v_cvt_pk_bf16_f32 v140, v140, v141
	v_cvt_pk_bf16_f32 v141, v142, v143
	v_cvt_pk_bf16_f32 v142, v144, v145
	v_cvt_pk_bf16_f32 v143, v146, v147
	global_store_dwordx4 v[156:157], v[140:143], off offset:2048 sc1
	v_lshl_add_u64 v[156:157], v[156:157], 0, s[20:21]
	s_waitcnt vmcnt(7)
	v_lshlrev_b32_e32 v196, 16, v22
	v_and_b32_e32 v197, 0xffff0000, v22
	v_lshlrev_b32_e32 v198, 16, v23
	v_and_b32_e32 v199, 0xffff0000, v23
	v_lshlrev_b32_e32 v200, 16, v24
	v_and_b32_e32 v201, 0xffff0000, v24
	v_lshlrev_b32_e32 v202, 16, v25
	v_and_b32_e32 v203, 0xffff0000, v25
	v_mul_f32_e32 v140, v164, v196
	v_mul_f32_e32 v141, v165, v197
	v_mul_f32_e32 v142, v166, v198
	v_mul_f32_e32 v143, v167, v199
	v_mul_f32_e32 v144, v168, v200
	v_mul_f32_e32 v145, v169, v201
	v_mul_f32_e32 v146, v170, v202
	v_mul_f32_e32 v147, v171, v203
	v_fmac_f32_e32 v140, v172, v188
	v_fmac_f32_e32 v141, v173, v189
	v_fmac_f32_e32 v142, v174, v190
	v_fmac_f32_e32 v143, v175, v191
	v_fmac_f32_e32 v144, v176, v192
	v_fmac_f32_e32 v145, v177, v193
	v_fmac_f32_e32 v146, v178, v194
	v_fmac_f32_e32 v147, v179, v195
	v_fmac_f32_e32 v140, v180, v204
	v_fmac_f32_e32 v141, v181, v205
	v_fmac_f32_e32 v142, v182, v206
	v_fmac_f32_e32 v143, v183, v207
	v_fmac_f32_e32 v144, v184, v208
	v_fmac_f32_e32 v145, v185, v209
	v_fmac_f32_e32 v146, v186, v210
	v_fmac_f32_e32 v147, v187, v211
	v_lshlrev_b32_e32 v150, 16, v6
	v_and_b32_e32 v151, 0xffff0000, v6
	v_mul_f32_e32 v140, v150, v140
	v_mul_f32_e32 v141, v151, v141
	v_lshlrev_b32_e32 v150, 16, v7
	v_and_b32_e32 v151, 0xffff0000, v7
	v_mul_f32_e32 v142, v150, v142
	v_mul_f32_e32 v143, v151, v143
	v_lshlrev_b32_e32 v150, 16, v8
	v_and_b32_e32 v151, 0xffff0000, v8
	v_mul_f32_e32 v144, v150, v144
	v_mul_f32_e32 v145, v151, v145
	v_lshlrev_b32_e32 v150, 16, v9
	v_and_b32_e32 v151, 0xffff0000, v9
	v_mul_f32_e32 v146, v150, v146
	v_mul_f32_e32 v147, v151, v147
	v_mul_f32_e32 v148, v140, v140
	v_fmac_f32_e32 v148, v141, v141
	v_fmac_f32_e32 v148, v142, v142
	v_fmac_f32_e32 v148, v143, v143
	v_fmac_f32_e32 v148, v144, v144
	v_fmac_f32_e32 v148, v145, v145
	v_fmac_f32_e32 v148, v146, v146
	v_fmac_f32_e32 v148, v147, v147
	v_mad_i64_i32 v[152:153], vcc, s41, v221, v[58:59]
	s_add_u32 s41, s41, 1
	global_load_dwordx4 v[6:9], v[152:153], off offset:1536
	global_load_dwordx4 v[22:25], v[152:153], off offset:2560
	s_nop 1
	v_add_f32_dpp v148, v148, v148 quad_perm:[1,0,3,2] row_mask:0xf bank_mask:0xf
	s_nop 1
	v_add_f32_dpp v148, v148, v148 quad_perm:[2,3,0,1] row_mask:0xf bank_mask:0xf
	s_nop 1
	v_add_f32_dpp v148, v148, v148 row_half_mirror row_mask:0xf bank_mask:0xf
	s_nop 1
	v_add_f32_dpp v148, v148, v148 row_mirror row_mask:0xf bank_mask:0xf
	s_nop 1
	v_add_f32_dpp v148, v148, v148 row_bcast:15 row_mask:0xa bank_mask:0xf
	s_nop 1
	v_add_f32_dpp v148, v148, v148 row_bcast:31 row_mask:0xc bank_mask:0xf
	s_nop 0
	v_readlane_b32 s0, v148, 63
	s_nop 1
	v_mov_b32_e32 v148, s0
	v_fmamk_f32 v148, v148, 0x3b000000, v162
	v_mul_f32_e32 v150, 0x4b800000, v148
	v_cmp_gt_f32_e32 vcc, s31, v148
	s_nop 1
	v_cndmask_b32_e32 v148, v148, v150, vcc
	v_rsq_f32_e32 v148, v148
	s_nop 0
	v_mul_f32_e32 v150, 0x45800000, v148
	v_cndmask_b32_e32 v149, v148, v150, vcc
	v_mul_f32_e32 v140, v149, v140
	v_mul_f32_e32 v141, v149, v141
	v_mul_f32_e32 v142, v149, v142
	v_mul_f32_e32 v143, v149, v143
	v_mul_f32_e32 v144, v149, v144
	v_mul_f32_e32 v145, v149, v145
	v_mul_f32_e32 v146, v149, v146
	v_mul_f32_e32 v147, v149, v147
	v_cvt_pk_bf16_f32 v140, v140, v141
	v_cvt_pk_bf16_f32 v141, v142, v143
	v_cvt_pk_bf16_f32 v142, v144, v145
	v_cvt_pk_bf16_f32 v143, v146, v147
	global_store_dwordx4 v[156:157], v[140:143], off sc1
	s_waitcnt vmcnt(7)
; __device__ __forceinline__ unsigned cvt_pk_bf16(float lo, float hi) { unsigned r; asm volatile("v_cvt_pk_bf16_f32 %0, %1, %2" : "=v"(r) : "v"(lo), "v"(hi)); return r; }
; __device__ __forceinline__ float bf_lo(unsigned w) { return __uint_as_float(w << 16); }
; __device__ __forceinline__ float bf_hi(unsigned w) { return __uint_as_float(w & 0xffff0000u); }
; __global__ void __launch_bounds__(512, 2) trunk_fwd(Args args) {
;     ...
;                 for (int rr = 0; rr < 16; ++rr) {
;                     const int r = r0 + rr;
;                     const u32x4 gb = gb_n, gu = gu_n; const f32x4 pv4 = pv_n;
;                     if (rr < 15) { gb_n = *(const u32x4*)(Z + (size_t)(r + 1) * INP + 768 + c0); gu_n = *(const u32x4*)(Z + (size_t)(r + 1) * INP + 1280 + c0);
;                                    pv_n = *(const f32x4*)(pl + (size_t)(r + 1) * PLE + lane * 4); }
;                     float cv[8], uu[8]; float ss = 0.f;
; #pragma unroll
;                     for (int i = 0; i < 4; ++i) {
;                         uu[2 * i] = bf_lo(gu[i]); uu[2 * i + 1] = bf_hi(gu[i]);
;                         cv[2 * i] = bf_lo(gb[i]) * (w0[2 * i] * uu[2 * i] + w1[2 * i] * u1[2 * i] + w2[2 * i] * u2[2 * i]);
;                         cv[2 * i + 1] = bf_hi(gb[i]) * (w0[2 * i + 1] * uu[2 * i + 1] + w1[2 * i + 1] * u1[2 * i + 1] + w2[2 * i + 1] * u2[2 * i + 1]);
;                     }
; #pragma unroll
;                     for (int i = 0; i < 8; ++i) { ss += cv[i] * cv[i]; u2[i] = u1[i]; u1[i] = uu[i]; }
;                     ss = wave_sum(ss);
;                     const float rc = rsqrtf(ss * (1.0f / 512.0f) + EPS);
;                     u32x4 oc;
; #pragma unroll
;                     for (int i = 0; i < 4; ++i) oc[i] = cvt_pk_bf16(cv[2 * i] * rc, cv[2 * i + 1] * rc);
;                     *(u32x4*)(MIX + (size_t)r * 1024 + 512 + c0) = oc;
	v_lshlrev_b32_e32 v204, 16, v26
	v_and_b32_e32 v205, 0xffff0000, v26
	v_lshlrev_b32_e32 v206, 16, v27
	v_and_b32_e32 v207, 0xffff0000, v27
	v_lshlrev_b32_e32 v208, 16, v28
	v_and_b32_e32 v209, 0xffff0000, v28
	v_lshlrev_b32_e32 v210, 16, v29
	v_and_b32_e32 v211, 0xffff0000, v29
	v_mul_f32_e32 v140, v164, v204
	v_mul_f32_e32 v141, v165, v205
	v_mul_f32_e32 v142, v166, v206
	v_mul_f32_e32 v143, v167, v207
	v_mul_f32_e32 v144, v168, v208
	v_mul_f32_e32 v145, v169, v209
	v_mul_f32_e32 v146, v170, v210
	v_mul_f32_e32 v147, v171, v211
	v_fmac_f32_e32 v140, v172, v196
	v_fmac_f32_e32 v141, v173, v197
	v_fmac_f32_e32 v142, v174, v198
	v_fmac_f32_e32 v143, v175, v199
	v_fmac_f32_e32 v144, v176, v200
	v_fmac_f32_e32 v145, v177, v201
	v_fmac_f32_e32 v146, v178, v202
	v_fmac_f32_e32 v147, v179, v203
	v_fmac_f32_e32 v140, v180, v188
	v_fmac_f32_e32 v141, v181, v189
	v_fmac_f32_e32 v142, v182, v190
	v_fmac_f32_e32 v143, v183, v191
	v_fmac_f32_e32 v144, v184, v192
	v_fmac_f32_e32 v145, v185, v193
	v_fmac_f32_e32 v146, v186, v194
	v_fmac_f32_e32 v147, v187, v195
	v_lshlrev_b32_e32 v150, 16, v10
	v_and_b32_e32 v151, 0xffff0000, v10
	v_mul_f32_e32 v140, v150, v140
	v_mul_f32_e32 v141, v151, v141
	v_lshlrev_b32_e32 v150, 16, v11
	v_and_b32_e32 v151, 0xffff0000, v11
	v_mul_f32_e32 v142, v150, v142
	v_mul_f32_e32 v143, v151, v143
	v_lshlrev_b32_e32 v150, 16, v12
	v_and_b32_e32 v151, 0xffff0000, v12
	v_mul_f32_e32 v144, v150, v144
	v_mul_f32_e32 v145, v151, v145
	v_lshlrev_b32_e32 v150, 16, v13
	v_and_b32_e32 v151, 0xffff0000, v13
	v_mul_f32_e32 v146, v150, v146
	v_mul_f32_e32 v147, v151, v147
	v_mul_f32_e32 v148, v140, v140
	v_fmac_f32_e32 v148, v141, v141
	v_fmac_f32_e32 v148, v142, v142
	v_fmac_f32_e32 v148, v143, v143
	v_fmac_f32_e32 v148, v144, v144
	v_fmac_f32_e32 v148, v145, v145
	v_fmac_f32_e32 v148, v146, v146
	v_fmac_f32_e32 v148, v147, v147
	v_mad_i64_i32 v[152:153], vcc, s41, v221, v[58:59]
	s_add_u32 s41, s41, 1
	global_load_dwordx4 v[10:13], v[152:153], off offset:1536
	global_load_dwordx4 v[26:29], v[152:153], off offset:2560
	s_nop 1
	v_add_f32_dpp v148, v148, v148 quad_perm:[1,0,3,2] row_mask:0xf bank_mask:0xf
	s_nop 1
	v_add_f32_dpp v148, v148, v148 quad_perm:[2,3,0,1] row_mask:0xf bank_mask:0xf
	s_nop 1
	v_add_f32_dpp v148, v148, v148 row_half_mirror row_mask:0xf bank_mask:0xf
	s_nop 1
	v_add_f32_dpp v148, v148, v148 row_mirror row_mask:0xf bank_mask:0xf
	s_nop 1
	v_add_f32_dpp v148, v148, v148 row_bcast:15 row_mask:0xa bank_mask:0xf
	s_nop 1
	v_add_f32_dpp v148, v148, v148 row_bcast:31 row_mask:0xc bank_mask:0xf
	s_nop 0
	v_readlane_b32 s0, v148, 63
	s_nop 1
	v_mov_b32_e32 v148, s0
	v_fmamk_f32 v148, v148, 0x3b000000, v162
	v_mul_f32_e32 v150, 0x4b800000, v148
	v_cmp_gt_f32_e32 vcc, s31, v148
	s_nop 1
	v_cndmask_b32_e32 v148, v148, v150, vcc
	v_rsq_f32_e32 v148, v148
	s_nop 0
	v_mul_f32_e32 v150, 0x45800000, v148
	v_cndmask_b32_e32 v149, v148, v150, vcc
	v_mul_f32_e32 v140, v149, v140
	v_mul_f32_e32 v141, v149, v141
	v_mul_f32_e32 v142, v149, v142
	v_mul_f32_e32 v143, v149, v143
	v_mul_f32_e32 v144, v149, v144
	v_mul_f32_e32 v145, v149, v145
	v_mul_f32_e32 v146, v149, v146
	v_mul_f32_e32 v147, v149, v147
	v_cvt_pk_bf16_f32 v140, v140, v141
	v_cvt_pk_bf16_f32 v141, v142, v143
	v_cvt_pk_bf16_f32 v142, v144, v145
	v_cvt_pk_bf16_f32 v143, v146, v147
	global_store_dwordx4 v[156:157], v[140:143], off offset:2048 sc1
	v_lshl_add_u64 v[156:157], v[156:157], 0, s[20:21]
	s_waitcnt vmcnt(7)
	v_lshlrev_b32_e32 v188, 16, v18
	v_and_b32_e32 v189, 0xffff0000, v18
	v_lshlrev_b32_e32 v190, 16, v19
	v_and_b32_e32 v191, 0xffff0000, v19
	v_lshlrev_b32_e32 v192, 16, v20
	v_and_b32_e32 v193, 0xffff0000, v20
	v_lshlrev_b32_e32 v194, 16, v21
	v_and_b32_e32 v195, 0xffff0000, v21
	v_mul_f32_e32 v140, v164, v188
	v_mul_f32_e32 v141, v165, v189
	v_mul_f32_e32 v142, v166, v190
	v_mul_f32_e32 v143, v167, v191
	v_mul_f32_e32 v144, v168, v192
	v_mul_f32_e32 v145, v169, v193
	v_mul_f32_e32 v146, v170, v194
	v_mul_f32_e32 v147, v171, v195
	v_fmac_f32_e32 v140, v172, v204
	v_fmac_f32_e32 v141, v173, v205
	v_fmac_f32_e32 v142, v174, v206
	v_fmac_f32_e32 v143, v175, v207
	v_fmac_f32_e32 v144, v176, v208
	v_fmac_f32_e32 v145, v177, v209
	v_fmac_f32_e32 v146, v178, v210
	v_fmac_f32_e32 v147, v179, v211
	v_fmac_f32_e32 v140, v180, v196
	v_fmac_f32_e32 v141, v181, v197
	v_fmac_f32_e32 v142, v182, v198
	v_fmac_f32_e32 v143, v183, v199
	v_fmac_f32_e32 v144, v184, v200
	v_fmac_f32_e32 v145, v185, v201
	v_fmac_f32_e32 v146, v186, v202
	v_fmac_f32_e32 v147, v187, v203
	v_lshlrev_b32_e32 v150, 16, v2
	v_and_b32_e32 v151, 0xffff0000, v2
	v_mul_f32_e32 v140, v150, v140
	v_mul_f32_e32 v141, v151, v141
	v_lshlrev_b32_e32 v150, 16, v3
	v_and_b32_e32 v151, 0xffff0000, v3
	v_mul_f32_e32 v142, v150, v142
	v_mul_f32_e32 v143, v151, v143
	v_lshlrev_b32_e32 v150, 16, v4
	v_and_b32_e32 v151, 0xffff0000, v4
	v_mul_f32_e32 v144, v150, v144
	v_mul_f32_e32 v145, v151, v145
	v_lshlrev_b32_e32 v150, 16, v5
	v_and_b32_e32 v151, 0xffff0000, v5
	v_mul_f32_e32 v146, v150, v146
	v_mul_f32_e32 v147, v151, v147
	v_mul_f32_e32 v148, v140, v140
	v_fmac_f32_e32 v148, v141, v141
	v_fmac_f32_e32 v148, v142, v142
	v_fmac_f32_e32 v148, v143, v143
	v_fmac_f32_e32 v148, v144, v144
	v_fmac_f32_e32 v148, v145, v145
	v_fmac_f32_e32 v148, v146, v146
	v_fmac_f32_e32 v148, v147, v147
	v_mad_i64_i32 v[152:153], vcc, s41, v221, v[58:59]
	s_add_u32 s41, s41, 1
	global_load_dwordx4 v[2:5], v[152:153], off offset:1536
	global_load_dwordx4 v[18:21], v[152:153], off offset:2560
	s_nop 1
	v_add_f32_dpp v148, v148, v148 quad_perm:[1,0,3,2] row_mask:0xf bank_mask:0xf
	s_nop 1
	v_add_f32_dpp v148, v148, v148 quad_perm:[2,3,0,1] row_mask:0xf bank_mask:0xf
	s_nop 1
	v_add_f32_dpp v148, v148, v148 row_half_mirror row_mask:0xf bank_mask:0xf
	s_nop 1
	v_add_f32_dpp v148, v148, v148 row_mirror row_mask:0xf bank_mask:0xf
	s_nop 1
	v_add_f32_dpp v148, v148, v148 row_bcast:15 row_mask:0xa bank_mask:0xf
	s_nop 1
	v_add_f32_dpp v148, v148, v148 row_bcast:31 row_mask:0xc bank_mask:0xf
	s_nop 0
	v_readlane_b32 s0, v148, 63
	s_nop 1
	v_mov_b32_e32 v148, s0
	v_fmamk_f32 v148, v148, 0x3b000000, v162
	v_mul_f32_e32 v150, 0x4b800000, v148
	v_cmp_gt_f32_e32 vcc, s31, v148
	s_nop 1
	v_cndmask_b32_e32 v148, v148, v150, vcc
	v_rsq_f32_e32 v148, v148
	s_nop 0
	v_mul_f32_e32 v150, 0x45800000, v148
	v_cndmask_b32_e32 v149, v148, v150, vcc
	v_mul_f32_e32 v140, v149, v140
	v_mul_f32_e32 v141, v149, v141
	v_mul_f32_e32 v142, v149, v142
	v_mul_f32_e32 v143, v149, v143
	v_mul_f32_e32 v144, v149, v144
	v_mul_f32_e32 v145, v149, v145
	v_mul_f32_e32 v146, v149, v146
	v_mul_f32_e32 v147, v149, v147
	v_cvt_pk_bf16_f32 v140, v140, v141
	v_cvt_pk_bf16_f32 v141, v142, v143
	v_cvt_pk_bf16_f32 v142, v144, v145
	v_cvt_pk_bf16_f32 v143, v146, v147
	global_store_dwordx4 v[156:157], v[140:143], off sc1
	s_waitcnt vmcnt(7)
; __device__ __forceinline__ unsigned cvt_pk_bf16(float lo, float hi) { unsigned r; asm volatile("v_cvt_pk_bf16_f32 %0, %1, %2" : "=v"(r) : "v"(lo), "v"(hi)); return r; }
; __device__ __forceinline__ float bf_lo(unsigned w) { return __uint_as_float(w << 16); }
; __device__ __forceinline__ float bf_hi(unsigned w) { return __uint_as_float(w & 0xffff0000u); }
; __global__ void __launch_bounds__(512, 2) trunk_fwd(Args args) {
;     ...
;                 for (int rr = 0; rr < 16; ++rr) {
;                     const int r = r0 + rr;
;                     const u32x4 gb = gb_n, gu = gu_n; const f32x4 pv4 = pv_n;
;                     if (rr < 15) { gb_n = *(const u32x4*)(Z + (size_t)(r + 1) * INP + 768 + c0); gu_n = *(const u32x4*)(Z + (size_t)(r + 1) * INP + 1280 + c0);
;                                    pv_n = *(const f32x4*)(pl + (size_t)(r + 1) * PLE + lane * 4); }
;                     float cv[8], uu[8]; float ss = 0.f;
; #pragma unroll
;                     for (int i = 0; i < 4; ++i) {
;                         uu[2 * i] = bf_lo(gu[i]); uu[2 * i + 1] = bf_hi(gu[i]);
;                         cv[2 * i] = bf_lo(gb[i]) * (w0[2 * i] * uu[2 * i] + w1[2 * i] * u1[2 * i] + w2[2 * i] * u2[2 * i]);
;                         cv[2 * i + 1] = bf_hi(gb[i]) * (w0[2 * i + 1] * uu[2 * i + 1] + w1[2 * i + 1] * u1[2 * i + 1] + w2[2 * i + 1] * u2[2 * i + 1]);
;                     }
; #pragma unroll
;                     for (int i = 0; i < 8; ++i) { ss += cv[i] * cv[i]; u2[i] = u1[i]; u1[i] = uu[i]; }
;                     ss = wave_sum(ss);
;                     const float rc = rsqrtf(ss * (1.0f / 512.0f) + EPS);
;                     u32x4 oc;
; #pragma unroll
;                     for (int i = 0; i < 4; ++i) oc[i] = cvt_pk_bf16(cv[2 * i] * rc, cv[2 * i + 1] * rc);
;                     *(u32x4*)(MIX + (size_t)r * 1024 + 512 + c0) = oc;
	v_lshlrev_b32_e32 v196, 16, v22
	v_and_b32_e32 v197, 0xffff0000, v22
	v_lshlrev_b32_e32 v198, 16, v23
	v_and_b32_e32 v199, 0xffff0000, v23
	v_lshlrev_b32_e32 v200, 16, v24
	v_and_b32_e32 v201, 0xffff0000, v24
	v_lshlrev_b32_e32 v202, 16, v25
	v_and_b32_e32 v203, 0xffff0000, v25
	v_mul_f32_e32 v140, v164, v196
	v_mul_f32_e32 v141, v165, v197
	v_mul_f32_e32 v142, v166, v198
	v_mul_f32_e32 v143, v167, v199
	v_mul_f32_e32 v144, v168, v200
	v_mul_f32_e32 v145, v169, v201
	v_mul_f32_e32 v146, v170, v202
	v_mul_f32_e32 v147, v171, v203
	v_fmac_f32_e32 v140, v172, v188
	v_fmac_f32_e32 v141, v173, v189
	v_fmac_f32_e32 v142, v174, v190
	v_fmac_f32_e32 v143, v175, v191
	v_fmac_f32_e32 v144, v176, v192
	v_fmac_f32_e32 v145, v177, v193
	v_fmac_f32_e32 v146, v178, v194
	v_fmac_f32_e32 v147, v179, v195
	v_fmac_f32_e32 v140, v180, v204
	v_fmac_f32_e32 v141, v181, v205
	v_fmac_f32_e32 v142, v182, v206
	v_fmac_f32_e32 v143, v183, v207
	v_fmac_f32_e32 v144, v184, v208
	v_fmac_f32_e32 v145, v185, v209
	v_fmac_f32_e32 v146, v186, v210
	v_fmac_f32_e32 v147, v187, v211
	v_lshlrev_b32_e32 v150, 16, v6
	v_and_b32_e32 v151, 0xffff0000, v6
	v_mul_f32_e32 v140, v150, v140
	v_mul_f32_e32 v141, v151, v141
	v_lshlrev_b32_e32 v150, 16, v7
	v_and_b32_e32 v151, 0xffff0000, v7
	v_mul_f32_e32 v142, v150, v142
	v_mul_f32_e32 v143, v151, v143
	v_lshlrev_b32_e32 v150, 16, v8
	v_and_b32_e32 v151, 0xffff0000, v8
	v_mul_f32_e32 v144, v150, v144
	v_mul_f32_e32 v145, v151, v145
	v_lshlrev_b32_e32 v150, 16, v9
	v_and_b32_e32 v151, 0xffff0000, v9
	v_mul_f32_e32 v146, v150, v146
	v_mul_f32_e32 v147, v151, v147
	v_mul_f32_e32 v148, v140, v140
	v_fmac_f32_e32 v148, v141, v141
	v_fmac_f32_e32 v148, v142, v142
	v_fmac_f32_e32 v148, v143, v143
	v_fmac_f32_e32 v148, v144, v144
	v_fmac_f32_e32 v148, v145, v145
	v_fmac_f32_e32 v148, v146, v146
	v_fmac_f32_e32 v148, v147, v147
	v_mad_i64_i32 v[152:153], vcc, s41, v221, v[58:59]
	s_add_u32 s41, s41, 1
	global_load_dwordx4 v[6:9], v[152:153], off offset:1536
	global_load_dwordx4 v[22:25], v[152:153], off offset:2560
	s_nop 1
	v_add_f32_dpp v148, v148, v148 quad_perm:[1,0,3,2] row_mask:0xf bank_mask:0xf
	s_nop 1
	v_add_f32_dpp v148, v148, v148 quad_perm:[2,3,0,1] row_mask:0xf bank_mask:0xf
	s_nop 1
	v_add_f32_dpp v148, v148, v148 row_half_mirror row_mask:0xf bank_mask:0xf
	s_nop 1
	v_add_f32_dpp v148, v148, v148 row_mirror row_mask:0xf bank_mask:0xf
	s_nop 1
	v_add_f32_dpp v148, v148, v148 row_bcast:15 row_mask:0xa bank_mask:0xf
	s_nop 1
	v_add_f32_dpp v148, v148, v148 row_bcast:31 row_mask:0xc bank_mask:0xf
	s_nop 0
	v_readlane_b32 s0, v148, 63
	s_nop 1
	v_mov_b32_e32 v148, s0
	v_fmamk_f32 v148, v148, 0x3b000000, v162
	v_mul_f32_e32 v150, 0x4b800000, v148
	v_cmp_gt_f32_e32 vcc, s31, v148
	s_nop 1
	v_cndmask_b32_e32 v148, v148, v150, vcc
	v_rsq_f32_e32 v148, v148
	s_nop 0
	v_mul_f32_e32 v150, 0x45800000, v148
	v_cndmask_b32_e32 v149, v148, v150, vcc
	v_mul_f32_e32 v140, v149, v140
	v_mul_f32_e32 v141, v149, v141
	v_mul_f32_e32 v142, v149, v142
	v_mul_f32_e32 v143, v149, v143
	v_mul_f32_e32 v144, v149, v144
	v_mul_f32_e32 v145, v149, v145
	v_mul_f32_e32 v146, v149, v146
	v_mul_f32_e32 v147, v149, v147
	v_cvt_pk_bf16_f32 v140, v140, v141
	v_cvt_pk_bf16_f32 v141, v142, v143
	v_cvt_pk_bf16_f32 v142, v144, v145
	v_cvt_pk_bf16_f32 v143, v146, v147
	global_store_dwordx4 v[156:157], v[140:143], off offset:2048 sc1
	v_lshl_add_u64 v[156:157], v[156:157], 0, s[20:21]
	s_waitcnt vmcnt(7)
	v_lshlrev_b32_e32 v204, 16, v26
	v_and_b32_e32 v205, 0xffff0000, v26
	v_lshlrev_b32_e32 v206, 16, v27
	v_and_b32_e32 v207, 0xffff0000, v27
	v_lshlrev_b32_e32 v208, 16, v28
	v_and_b32_e32 v209, 0xffff0000, v28
	v_lshlrev_b32_e32 v210, 16, v29
	v_and_b32_e32 v211, 0xffff0000, v29
	v_mul_f32_e32 v140, v164, v204
	v_mul_f32_e32 v141, v165, v205
	v_mul_f32_e32 v142, v166, v206
	v_mul_f32_e32 v143, v167, v207
	v_mul_f32_e32 v144, v168, v208
	v_mul_f32_e32 v145, v169, v209
	v_mul_f32_e32 v146, v170, v210
	v_mul_f32_e32 v147, v171, v211
	v_fmac_f32_e32 v140, v172, v196
	v_fmac_f32_e32 v141, v173, v197
	v_fmac_f32_e32 v142, v174, v198
	v_fmac_f32_e32 v143, v175, v199
	v_fmac_f32_e32 v144, v176, v200
	v_fmac_f32_e32 v145, v177, v201
	v_fmac_f32_e32 v146, v178, v202
	v_fmac_f32_e32 v147, v179, v203
	v_fmac_f32_e32 v140, v180, v188
	v_fmac_f32_e32 v141, v181, v189
	v_fmac_f32_e32 v142, v182, v190
	v_fmac_f32_e32 v143, v183, v191
	v_fmac_f32_e32 v144, v184, v192
	v_fmac_f32_e32 v145, v185, v193
	v_fmac_f32_e32 v146, v186, v194
	v_fmac_f32_e32 v147, v187, v195
	v_lshlrev_b32_e32 v150, 16, v10
	v_and_b32_e32 v151, 0xffff0000, v10
	v_mul_f32_e32 v140, v150, v140
	v_mul_f32_e32 v141, v151, v141
	v_lshlrev_b32_e32 v150, 16, v11
	v_and_b32_e32 v151, 0xffff0000, v11
	v_mul_f32_e32 v142, v150, v142
	v_mul_f32_e32 v143, v151, v143
	v_lshlrev_b32_e32 v150, 16, v12
	v_and_b32_e32 v151, 0xffff0000, v12
	v_mul_f32_e32 v144, v150, v144
	v_mul_f32_e32 v145, v151, v145
	v_lshlrev_b32_e32 v150, 16, v13
	v_and_b32_e32 v151, 0xffff0000, v13
	v_mul_f32_e32 v146, v150, v146
	v_mul_f32_e32 v147, v151, v147
	v_mul_f32_e32 v148, v140, v140
	v_fmac_f32_e32 v148, v141, v141
	v_fmac_f32_e32 v148, v142, v142
	v_fmac_f32_e32 v148, v143, v143
	v_fmac_f32_e32 v148, v144, v144
	v_fmac_f32_e32 v148, v145, v145
	v_fmac_f32_e32 v148, v146, v146
	v_fmac_f32_e32 v148, v147, v147
	v_mad_i64_i32 v[152:153], vcc, s41, v221, v[58:59]
	s_add_u32 s41, s41, 1
	global_load_dwordx4 v[10:13], v[152:153], off offset:1536
	global_load_dwordx4 v[26:29], v[152:153], off offset:2560
	s_nop 1
	v_add_f32_dpp v148, v148, v148 quad_perm:[1,0,3,2] row_mask:0xf bank_mask:0xf
	s_nop 1
	v_add_f32_dpp v148, v148, v148 quad_perm:[2,3,0,1] row_mask:0xf bank_mask:0xf
	s_nop 1
	v_add_f32_dpp v148, v148, v148 row_half_mirror row_mask:0xf bank_mask:0xf
	s_nop 1
	v_add_f32_dpp v148, v148, v148 row_mirror row_mask:0xf bank_mask:0xf
	s_nop 1
	v_add_f32_dpp v148, v148, v148 row_bcast:15 row_mask:0xa bank_mask:0xf
	s_nop 1
	v_add_f32_dpp v148, v148, v148 row_bcast:31 row_mask:0xc bank_mask:0xf
	s_nop 0
	v_readlane_b32 s0, v148, 63
	s_nop 1
	v_mov_b32_e32 v148, s0
	v_fmamk_f32 v148, v148, 0x3b000000, v162
	v_mul_f32_e32 v150, 0x4b800000, v148
	v_cmp_gt_f32_e32 vcc, s31, v148
	s_nop 1
	v_cndmask_b32_e32 v148, v148, v150, vcc
	v_rsq_f32_e32 v148, v148
	s_nop 0
	v_mul_f32_e32 v150, 0x45800000, v148
	v_cndmask_b32_e32 v149, v148, v150, vcc
	v_mul_f32_e32 v140, v149, v140
	v_mul_f32_e32 v141, v149, v141
	v_mul_f32_e32 v142, v149, v142
	v_mul_f32_e32 v143, v149, v143
	v_mul_f32_e32 v144, v149, v144
	v_mul_f32_e32 v145, v149, v145
	v_mul_f32_e32 v146, v149, v146
	v_mul_f32_e32 v147, v149, v147
	v_cvt_pk_bf16_f32 v140, v140, v141
	v_cvt_pk_bf16_f32 v141, v142, v143
	v_cvt_pk_bf16_f32 v142, v144, v145
	v_cvt_pk_bf16_f32 v143, v146, v147
	global_store_dwordx4 v[156:157], v[140:143], off sc1
	s_waitcnt vmcnt(7)
; __device__ __forceinline__ unsigned cvt_pk_bf16(float lo, float hi) { unsigned r; asm volatile("v_cvt_pk_bf16_f32 %0, %1, %2" : "=v"(r) : "v"(lo), "v"(hi)); return r; }
; __device__ __forceinline__ float bf_lo(unsigned w) { return __uint_as_float(w << 16); }
; __device__ __forceinline__ float bf_hi(unsigned w) { return __uint_as_float(w & 0xffff0000u); }
; __global__ void __launch_bounds__(512, 2) trunk_fwd(Args args) {
;     ...
;                 for (int rr = 0; rr < 16; ++rr) {
;                     const int r = r0 + rr;
;                     const u32x4 gb = gb_n, gu = gu_n; const f32x4 pv4 = pv_n;
;                     if (rr < 15) { gb_n = *(const u32x4*)(Z + (size_t)(r + 1) * INP + 768 + c0); gu_n = *(const u32x4*)(Z + (size_t)(r + 1) * INP + 1280 + c0);
;                                    pv_n = *(const f32x4*)(pl + (size_t)(r + 1) * PLE + lane * 4); }
;                     float cv[8], uu[8]; float ss = 0.f;
; #pragma unroll
;                     for (int i = 0; i < 4; ++i) {
;                         uu[2 * i] = bf_lo(gu[i]); uu[2 * i + 1] = bf_hi(gu[i]);
;                         cv[2 * i] = bf_lo(gb[i]) * (w0[2 * i] * uu[2 * i] + w1[2 * i] * u1[2 * i] + w2[2 * i] * u2[2 * i]);
;                         cv[2 * i + 1] = bf_hi(gb[i]) * (w0[2 * i + 1] * uu[2 * i + 1] + w1[2 * i + 1] * u1[2 * i + 1] + w2[2 * i + 1] * u2[2 * i + 1]);
;                     }
; #pragma unroll
;                     for (int i = 0; i < 8; ++i) { ss += cv[i] * cv[i]; u2[i] = u1[i]; u1[i] = uu[i]; }
;                     ss = wave_sum(ss);
;                     const float rc = rsqrtf(ss * (1.0f / 512.0f) + EPS);
;                     u32x4 oc;
; #pragma unroll
;                     for (int i = 0; i < 4; ++i) oc[i] = cvt_pk_bf16(cv[2 * i] * rc, cv[2 * i + 1] * rc);
;                     *(u32x4*)(MIX + (size_t)r * 1024 + 512 + c0) = oc;
	v_lshlrev_b32_e32 v188, 16, v18
	v_and_b32_e32 v189, 0xffff0000, v18
	v_lshlrev_b32_e32 v190, 16, v19
	v_and_b32_e32 v191, 0xffff0000, v19
	v_lshlrev_b32_e32 v192, 16, v20
	v_and_b32_e32 v193, 0xffff0000, v20
	v_lshlrev_b32_e32 v194, 16, v21
	v_and_b32_e32 v195, 0xffff0000, v21
	v_mul_f32_e32 v140, v164, v188
	v_mul_f32_e32 v141, v165, v189
	v_mul_f32_e32 v142, v166, v190
	v_mul_f32_e32 v143, v167, v191
	v_mul_f32_e32 v144, v168, v192
	v_mul_f32_e32 v145, v169, v193
	v_mul_f32_e32 v146, v170, v194
	v_mul_f32_e32 v147, v171, v195
	v_fmac_f32_e32 v140, v172, v204
	v_fmac_f32_e32 v141, v173, v205
	v_fmac_f32_e32 v142, v174, v206
	v_fmac_f32_e32 v143, v175, v207
	v_fmac_f32_e32 v144, v176, v208
	v_fmac_f32_e32 v145, v177, v209
	v_fmac_f32_e32 v146, v178, v210
	v_fmac_f32_e32 v147, v179, v211
	v_fmac_f32_e32 v140, v180, v196
	v_fmac_f32_e32 v141, v181, v197
	v_fmac_f32_e32 v142, v182, v198
	v_fmac_f32_e32 v143, v183, v199
	v_fmac_f32_e32 v144, v184, v200
	v_fmac_f32_e32 v145, v185, v201
	v_fmac_f32_e32 v146, v186, v202
	v_fmac_f32_e32 v147, v187, v203
	v_lshlrev_b32_e32 v150, 16, v2
	v_and_b32_e32 v151, 0xffff0000, v2
	v_mul_f32_e32 v140, v150, v140
	v_mul_f32_e32 v141, v151, v141
	v_lshlrev_b32_e32 v150, 16, v3
	v_and_b32_e32 v151, 0xffff0000, v3
	v_mul_f32_e32 v142, v150, v142
	v_mul_f32_e32 v143, v151, v143
	v_lshlrev_b32_e32 v150, 16, v4
	v_and_b32_e32 v151, 0xffff0000, v4
	v_mul_f32_e32 v144, v150, v144
	v_mul_f32_e32 v145, v151, v145
	v_lshlrev_b32_e32 v150, 16, v5
	v_and_b32_e32 v151, 0xffff0000, v5
	v_mul_f32_e32 v146, v150, v146
	v_mul_f32_e32 v147, v151, v147
	v_mul_f32_e32 v148, v140, v140
	v_fmac_f32_e32 v148, v141, v141
	v_fmac_f32_e32 v148, v142, v142
	v_fmac_f32_e32 v148, v143, v143
	v_fmac_f32_e32 v148, v144, v144
	v_fmac_f32_e32 v148, v145, v145
	v_fmac_f32_e32 v148, v146, v146
	v_fmac_f32_e32 v148, v147, v147
	v_mad_i64_i32 v[152:153], vcc, s41, v221, v[58:59]
	s_add_u32 s41, s41, 1
	global_load_dwordx4 v[2:5], v[152:153], off offset:1536
	global_load_dwordx4 v[18:21], v[152:153], off offset:2560
	s_nop 1
	v_add_f32_dpp v148, v148, v148 quad_perm:[1,0,3,2] row_mask:0xf bank_mask:0xf
	s_nop 1
	v_add_f32_dpp v148, v148, v148 quad_perm:[2,3,0,1] row_mask:0xf bank_mask:0xf
	s_nop 1
	v_add_f32_dpp v148, v148, v148 row_half_mirror row_mask:0xf bank_mask:0xf
	s_nop 1
	v_add_f32_dpp v148, v148, v148 row_mirror row_mask:0xf bank_mask:0xf
	s_nop 1
	v_add_f32_dpp v148, v148, v148 row_bcast:15 row_mask:0xa bank_mask:0xf
	s_nop 1
	v_add_f32_dpp v148, v148, v148 row_bcast:31 row_mask:0xc bank_mask:0xf
	s_nop 0
	v_readlane_b32 s0, v148, 63
	s_nop 1
	v_mov_b32_e32 v148, s0
	v_fmamk_f32 v148, v148, 0x3b000000, v162
	v_mul_f32_e32 v150, 0x4b800000, v148
	v_cmp_gt_f32_e32 vcc, s31, v148
	s_nop 1
	v_cndmask_b32_e32 v148, v148, v150, vcc
	v_rsq_f32_e32 v148, v148
	s_nop 0
	v_mul_f32_e32 v150, 0x45800000, v148
	v_cndmask_b32_e32 v149, v148, v150, vcc
	v_mul_f32_e32 v140, v149, v140
	v_mul_f32_e32 v141, v149, v141
	v_mul_f32_e32 v142, v149, v142
	v_mul_f32_e32 v143, v149, v143
	v_mul_f32_e32 v144, v149, v144
	v_mul_f32_e32 v145, v149, v145
	v_mul_f32_e32 v146, v149, v146
	v_mul_f32_e32 v147, v149, v147
	v_cvt_pk_bf16_f32 v140, v140, v141
	v_cvt_pk_bf16_f32 v141, v142, v143
	v_cvt_pk_bf16_f32 v142, v144, v145
	v_cvt_pk_bf16_f32 v143, v146, v147
	global_store_dwordx4 v[156:157], v[140:143], off offset:2048 sc1
	v_lshl_add_u64 v[156:157], v[156:157], 0, s[20:21]
	s_waitcnt vmcnt(7)
	v_lshlrev_b32_e32 v196, 16, v22
	v_and_b32_e32 v197, 0xffff0000, v22
	v_lshlrev_b32_e32 v198, 16, v23
	v_and_b32_e32 v199, 0xffff0000, v23
	v_lshlrev_b32_e32 v200, 16, v24
	v_and_b32_e32 v201, 0xffff0000, v24
	v_lshlrev_b32_e32 v202, 16, v25
	v_and_b32_e32 v203, 0xffff0000, v25
	v_mul_f32_e32 v140, v164, v196
	v_mul_f32_e32 v141, v165, v197
	v_mul_f32_e32 v142, v166, v198
	v_mul_f32_e32 v143, v167, v199
	v_mul_f32_e32 v144, v168, v200
	v_mul_f32_e32 v145, v169, v201
	v_mul_f32_e32 v146, v170, v202
	v_mul_f32_e32 v147, v171, v203
	v_fmac_f32_e32 v140, v172, v188
	v_fmac_f32_e32 v141, v173, v189
	v_fmac_f32_e32 v142, v174, v190
	v_fmac_f32_e32 v143, v175, v191
	v_fmac_f32_e32 v144, v176, v192
	v_fmac_f32_e32 v145, v177, v193
	v_fmac_f32_e32 v146, v178, v194
	v_fmac_f32_e32 v147, v179, v195
	v_fmac_f32_e32 v140, v180, v204
	v_fmac_f32_e32 v141, v181, v205
	v_fmac_f32_e32 v142, v182, v206
	v_fmac_f32_e32 v143, v183, v207
	v_fmac_f32_e32 v144, v184, v208
	v_fmac_f32_e32 v145, v185, v209
	v_fmac_f32_e32 v146, v186, v210
	v_fmac_f32_e32 v147, v187, v211
	v_lshlrev_b32_e32 v150, 16, v6
	v_and_b32_e32 v151, 0xffff0000, v6
	v_mul_f32_e32 v140, v150, v140
	v_mul_f32_e32 v141, v151, v141
	v_lshlrev_b32_e32 v150, 16, v7
	v_and_b32_e32 v151, 0xffff0000, v7
	v_mul_f32_e32 v142, v150, v142
	v_mul_f32_e32 v143, v151, v143
	v_lshlrev_b32_e32 v150, 16, v8
	v_and_b32_e32 v151, 0xffff0000, v8
	v_mul_f32_e32 v144, v150, v144
	v_mul_f32_e32 v145, v151, v145
	v_lshlrev_b32_e32 v150, 16, v9
	v_and_b32_e32 v151, 0xffff0000, v9
	v_mul_f32_e32 v146, v150, v146
	v_mul_f32_e32 v147, v151, v147
	v_mul_f32_e32 v148, v140, v140
	v_fmac_f32_e32 v148, v141, v141
	v_fmac_f32_e32 v148, v142, v142
	v_fmac_f32_e32 v148, v143, v143
	v_fmac_f32_e32 v148, v144, v144
	v_fmac_f32_e32 v148, v145, v145
	v_fmac_f32_e32 v148, v146, v146
	v_fmac_f32_e32 v148, v147, v147
	v_mad_i64_i32 v[152:153], vcc, s41, v221, v[58:59]
	s_add_u32 s41, s41, 1
	global_load_dwordx4 v[6:9], v[152:153], off offset:1536
	global_load_dwordx4 v[22:25], v[152:153], off offset:2560
	s_nop 1
	v_add_f32_dpp v148, v148, v148 quad_perm:[1,0,3,2] row_mask:0xf bank_mask:0xf
	s_nop 1
	v_add_f32_dpp v148, v148, v148 quad_perm:[2,3,0,1] row_mask:0xf bank_mask:0xf
	s_nop 1
	v_add_f32_dpp v148, v148, v148 row_half_mirror row_mask:0xf bank_mask:0xf
	s_nop 1
	v_add_f32_dpp v148, v148, v148 row_mirror row_mask:0xf bank_mask:0xf
	s_nop 1
	v_add_f32_dpp v148, v148, v148 row_bcast:15 row_mask:0xa bank_mask:0xf
	s_nop 1
	v_add_f32_dpp v148, v148, v148 row_bcast:31 row_mask:0xc bank_mask:0xf
	s_nop 0
	v_readlane_b32 s0, v148, 63
	s_nop 1
	v_mov_b32_e32 v148, s0
	v_fmamk_f32 v148, v148, 0x3b000000, v162
	v_mul_f32_e32 v150, 0x4b800000, v148
	v_cmp_gt_f32_e32 vcc, s31, v148
	s_nop 1
	v_cndmask_b32_e32 v148, v148, v150, vcc
	v_rsq_f32_e32 v148, v148
	s_nop 0
	v_mul_f32_e32 v150, 0x45800000, v148
	v_cndmask_b32_e32 v149, v148, v150, vcc
	v_mul_f32_e32 v140, v149, v140
	v_mul_f32_e32 v141, v149, v141
	v_mul_f32_e32 v142, v149, v142
	v_mul_f32_e32 v143, v149, v143
	v_mul_f32_e32 v144, v149, v144
	v_mul_f32_e32 v145, v149, v145
	v_mul_f32_e32 v146, v149, v146
	v_mul_f32_e32 v147, v149, v147
	v_cvt_pk_bf16_f32 v140, v140, v141
	v_cvt_pk_bf16_f32 v141, v142, v143
	v_cvt_pk_bf16_f32 v142, v144, v145
	v_cvt_pk_bf16_f32 v143, v146, v147
	global_store_dwordx4 v[156:157], v[140:143], off sc1
	s_waitcnt vmcnt(7)
; __device__ __forceinline__ unsigned cvt_pk_bf16(float lo, float hi) { unsigned r; asm volatile("v_cvt_pk_bf16_f32 %0, %1, %2" : "=v"(r) : "v"(lo), "v"(hi)); return r; }
; __device__ __forceinline__ float bf_lo(unsigned w) { return __uint_as_float(w << 16); }
; __device__ __forceinline__ float bf_hi(unsigned w) { return __uint_as_float(w & 0xffff0000u); }
; __global__ void __launch_bounds__(512, 2) trunk_fwd(Args args) {
;     ...
;                 for (int rr = 0; rr < 16; ++rr) {
;                     const int r = r0 + rr;
;                     const u32x4 gb = gb_n, gu = gu_n; const f32x4 pv4 = pv_n;
;                     if (rr < 15) { gb_n = *(const u32x4*)(Z + (size_t)(r + 1) * INP + 768 + c0); gu_n = *(const u32x4*)(Z + (size_t)(r + 1) * INP + 1280 + c0);
;                                    pv_n = *(const f32x4*)(pl + (size_t)(r + 1) * PLE + lane * 4); }
;                     float cv[8], uu[8]; float ss = 0.f;
; #pragma unroll
;                     for (int i = 0; i < 4; ++i) {
;                         uu[2 * i] = bf_lo(gu[i]); uu[2 * i + 1] = bf_hi(gu[i]);
;                         cv[2 * i] = bf_lo(gb[i]) * (w0[2 * i] * uu[2 * i] + w1[2 * i] * u1[2 * i] + w2[2 * i] * u2[2 * i]);
;                         cv[2 * i + 1] = bf_hi(gb[i]) * (w0[2 * i + 1] * uu[2 * i + 1] + w1[2 * i + 1] * u1[2 * i + 1] + w2[2 * i + 1] * u2[2 * i + 1]);
;                     }
; #pragma unroll
;                     for (int i = 0; i < 8; ++i) { ss += cv[i] * cv[i]; u2[i] = u1[i]; u1[i] = uu[i]; }
;                     ss = wave_sum(ss);
;                     const float rc = rsqrtf(ss * (1.0f / 512.0f) + EPS);
;                     u32x4 oc;
; #pragma unroll
;                     for (int i = 0; i < 4; ++i) oc[i] = cvt_pk_bf16(cv[2 * i] * rc, cv[2 * i + 1] * rc);
;                     *(u32x4*)(MIX + (size_t)r * 1024 + 512 + c0) = oc;
	v_lshlrev_b32_e32 v204, 16, v26
	v_and_b32_e32 v205, 0xffff0000, v26
	v_lshlrev_b32_e32 v206, 16, v27
	v_and_b32_e32 v207, 0xffff0000, v27
	v_lshlrev_b32_e32 v208, 16, v28
	v_and_b32_e32 v209, 0xffff0000, v28
	v_lshlrev_b32_e32 v210, 16, v29
	v_and_b32_e32 v211, 0xffff0000, v29
	v_mul_f32_e32 v140, v164, v204
	v_mul_f32_e32 v141, v165, v205
	v_mul_f32_e32 v142, v166, v206
	v_mul_f32_e32 v143, v167, v207
	v_mul_f32_e32 v144, v168, v208
	v_mul_f32_e32 v145, v169, v209
	v_mul_f32_e32 v146, v170, v210
	v_mul_f32_e32 v147, v171, v211
	v_fmac_f32_e32 v140, v172, v196
	v_fmac_f32_e32 v141, v173, v197
	v_fmac_f32_e32 v142, v174, v198
	v_fmac_f32_e32 v143, v175, v199
	v_fmac_f32_e32 v144, v176, v200
	v_fmac_f32_e32 v145, v177, v201
	v_fmac_f32_e32 v146, v178, v202
	v_fmac_f32_e32 v147, v179, v203
	v_fmac_f32_e32 v140, v180, v188
	v_fmac_f32_e32 v141, v181, v189
	v_fmac_f32_e32 v142, v182, v190
	v_fmac_f32_e32 v143, v183, v191
	v_fmac_f32_e32 v144, v184, v192
	v_fmac_f32_e32 v145, v185, v193
	v_fmac_f32_e32 v146, v186, v194
	v_fmac_f32_e32 v147, v187, v195
	v_lshlrev_b32_e32 v150, 16, v10
	v_and_b32_e32 v151, 0xffff0000, v10
	v_mul_f32_e32 v140, v150, v140
	v_mul_f32_e32 v141, v151, v141
	v_lshlrev_b32_e32 v150, 16, v11
	v_and_b32_e32 v151, 0xffff0000, v11
	v_mul_f32_e32 v142, v150, v142
	v_mul_f32_e32 v143, v151, v143
	v_lshlrev_b32_e32 v150, 16, v12
	v_and_b32_e32 v151, 0xffff0000, v12
	v_mul_f32_e32 v144, v150, v144
	v_mul_f32_e32 v145, v151, v145
	v_lshlrev_b32_e32 v150, 16, v13
	v_and_b32_e32 v151, 0xffff0000, v13
	v_mul_f32_e32 v146, v150, v146
	v_mul_f32_e32 v147, v151, v147
	v_mul_f32_e32 v148, v140, v140
	v_fmac_f32_e32 v148, v141, v141
	v_fmac_f32_e32 v148, v142, v142
	v_fmac_f32_e32 v148, v143, v143
	v_fmac_f32_e32 v148, v144, v144
	v_fmac_f32_e32 v148, v145, v145
	v_fmac_f32_e32 v148, v146, v146
	v_fmac_f32_e32 v148, v147, v147
	v_mad_i64_i32 v[152:153], vcc, s41, v221, v[58:59]
	s_add_u32 s41, s41, 1
	global_load_dwordx4 v[10:13], v[152:153], off offset:1536
	global_load_dwordx4 v[26:29], v[152:153], off offset:2560
	s_nop 1
	v_add_f32_dpp v148, v148, v148 quad_perm:[1,0,3,2] row_mask:0xf bank_mask:0xf
	s_nop 1
	v_add_f32_dpp v148, v148, v148 quad_perm:[2,3,0,1] row_mask:0xf bank_mask:0xf
	s_nop 1
	v_add_f32_dpp v148, v148, v148 row_half_mirror row_mask:0xf bank_mask:0xf
	s_nop 1
	v_add_f32_dpp v148, v148, v148 row_mirror row_mask:0xf bank_mask:0xf
	s_nop 1
	v_add_f32_dpp v148, v148, v148 row_bcast:15 row_mask:0xa bank_mask:0xf
	s_nop 1
	v_add_f32_dpp v148, v148, v148 row_bcast:31 row_mask:0xc bank_mask:0xf
	s_nop 0
	v_readlane_b32 s0, v148, 63
	s_nop 1
	v_mov_b32_e32 v148, s0
	v_fmamk_f32 v148, v148, 0x3b000000, v162
	v_mul_f32_e32 v150, 0x4b800000, v148
	v_cmp_gt_f32_e32 vcc, s31, v148
	s_nop 1
	v_cndmask_b32_e32 v148, v148, v150, vcc
	v_rsq_f32_e32 v148, v148
	s_nop 0
	v_mul_f32_e32 v150, 0x45800000, v148
	v_cndmask_b32_e32 v149, v148, v150, vcc
	v_mul_f32_e32 v140, v149, v140
	v_mul_f32_e32 v141, v149, v141
	v_mul_f32_e32 v142, v149, v142
	v_mul_f32_e32 v143, v149, v143
	v_mul_f32_e32 v144, v149, v144
	v_mul_f32_e32 v145, v149, v145
	v_mul_f32_e32 v146, v149, v146
	v_mul_f32_e32 v147, v149, v147
	v_cvt_pk_bf16_f32 v140, v140, v141
	v_cvt_pk_bf16_f32 v141, v142, v143
	v_cvt_pk_bf16_f32 v142, v144, v145
	v_cvt_pk_bf16_f32 v143, v146, v147
	global_store_dwordx4 v[156:157], v[140:143], off offset:2048 sc1
	v_lshl_add_u64 v[156:157], v[156:157], 0, s[20:21]
	s_waitcnt vmcnt(7)
	v_lshlrev_b32_e32 v188, 16, v18
	v_and_b32_e32 v189, 0xffff0000, v18
	v_lshlrev_b32_e32 v190, 16, v19
	v_and_b32_e32 v191, 0xffff0000, v19
	v_lshlrev_b32_e32 v192, 16, v20
	v_and_b32_e32 v193, 0xffff0000, v20
	v_lshlrev_b32_e32 v194, 16, v21
	v_and_b32_e32 v195, 0xffff0000, v21
	v_mul_f32_e32 v140, v164, v188
	v_mul_f32_e32 v141, v165, v189
	v_mul_f32_e32 v142, v166, v190
	v_mul_f32_e32 v143, v167, v191
	v_mul_f32_e32 v144, v168, v192
	v_mul_f32_e32 v145, v169, v193
	v_mul_f32_e32 v146, v170, v194
	v_mul_f32_e32 v147, v171, v195
	v_fmac_f32_e32 v140, v172, v204
	v_fmac_f32_e32 v141, v173, v205
	v_fmac_f32_e32 v142, v174, v206
	v_fmac_f32_e32 v143, v175, v207
	v_fmac_f32_e32 v144, v176, v208
	v_fmac_f32_e32 v145, v177, v209
	v_fmac_f32_e32 v146, v178, v210
	v_fmac_f32_e32 v147, v179, v211
	v_fmac_f32_e32 v140, v180, v196
	v_fmac_f32_e32 v141, v181, v197
	v_fmac_f32_e32 v142, v182, v198
	v_fmac_f32_e32 v143, v183, v199
	v_fmac_f32_e32 v144, v184, v200
	v_fmac_f32_e32 v145, v185, v201
	v_fmac_f32_e32 v146, v186, v202
	v_fmac_f32_e32 v147, v187, v203
	v_lshlrev_b32_e32 v150, 16, v2
	v_and_b32_e32 v151, 0xffff0000, v2
	v_mul_f32_e32 v140, v150, v140
	v_mul_f32_e32 v141, v151, v141
	v_lshlrev_b32_e32 v150, 16, v3
	v_and_b32_e32 v151, 0xffff0000, v3
	v_mul_f32_e32 v142, v150, v142
	v_mul_f32_e32 v143, v151, v143
	v_lshlrev_b32_e32 v150, 16, v4
	v_and_b32_e32 v151, 0xffff0000, v4
	v_mul_f32_e32 v144, v150, v144
	v_mul_f32_e32 v145, v151, v145
	v_lshlrev_b32_e32 v150, 16, v5
	v_and_b32_e32 v151, 0xffff0000, v5
	v_mul_f32_e32 v146, v150, v146
	v_mul_f32_e32 v147, v151, v147
	v_mul_f32_e32 v148, v140, v140
	v_fmac_f32_e32 v148, v141, v141
	v_fmac_f32_e32 v148, v142, v142
	v_fmac_f32_e32 v148, v143, v143
	v_fmac_f32_e32 v148, v144, v144
	v_fmac_f32_e32 v148, v145, v145
	v_fmac_f32_e32 v148, v146, v146
	v_fmac_f32_e32 v148, v147, v147
	v_mad_i64_i32 v[152:153], vcc, s41, v221, v[58:59]
	s_add_u32 s41, s41, 1
	global_load_dwordx4 v[2:5], v[152:153], off offset:1536
	global_load_dwordx4 v[18:21], v[152:153], off offset:2560
	s_nop 1
	v_add_f32_dpp v148, v148, v148 quad_perm:[1,0,3,2] row_mask:0xf bank_mask:0xf
	s_nop 1
	v_add_f32_dpp v148, v148, v148 quad_perm:[2,3,0,1] row_mask:0xf bank_mask:0xf
	s_nop 1
	v_add_f32_dpp v148, v148, v148 row_half_mirror row_mask:0xf bank_mask:0xf
	s_nop 1
	v_add_f32_dpp v148, v148, v148 row_mirror row_mask:0xf bank_mask:0xf
	s_nop 1
	v_add_f32_dpp v148, v148, v148 row_bcast:15 row_mask:0xa bank_mask:0xf
	s_nop 1
	v_add_f32_dpp v148, v148, v148 row_bcast:31 row_mask:0xc bank_mask:0xf
	s_nop 0
	v_readlane_b32 s0, v148, 63
	s_nop 1
	v_mov_b32_e32 v148, s0
	v_fmamk_f32 v148, v148, 0x3b000000, v162
	v_mul_f32_e32 v150, 0x4b800000, v148
	v_cmp_gt_f32_e32 vcc, s31, v148
	s_nop 1
	v_cndmask_b32_e32 v148, v148, v150, vcc
	v_rsq_f32_e32 v148, v148
	s_nop 0
	v_mul_f32_e32 v150, 0x45800000, v148
	v_cndmask_b32_e32 v149, v148, v150, vcc
	v_mul_f32_e32 v140, v149, v140
	v_mul_f32_e32 v141, v149, v141
	v_mul_f32_e32 v142, v149, v142
	v_mul_f32_e32 v143, v149, v143
	v_mul_f32_e32 v144, v149, v144
	v_mul_f32_e32 v145, v149, v145
	v_mul_f32_e32 v146, v149, v146
	v_mul_f32_e32 v147, v149, v147
	v_cvt_pk_bf16_f32 v140, v140, v141
	v_cvt_pk_bf16_f32 v141, v142, v143
	v_cvt_pk_bf16_f32 v142, v144, v145
	v_cvt_pk_bf16_f32 v143, v146, v147
	global_store_dwordx4 v[156:157], v[140:143], off sc1
	s_waitcnt vmcnt(7)
; __device__ __forceinline__ unsigned cvt_pk_bf16(float lo, float hi) { unsigned r; asm volatile("v_cvt_pk_bf16_f32 %0, %1, %2" : "=v"(r) : "v"(lo), "v"(hi)); return r; }
; __device__ __forceinline__ float bf_lo(unsigned w) { return __uint_as_float(w << 16); }
; __device__ __forceinline__ float bf_hi(unsigned w) { return __uint_as_float(w & 0xffff0000u); }
; __global__ void __launch_bounds__(512, 2) trunk_fwd(Args args) {
;     ...
;                 for (int rr = 0; rr < 16; ++rr) {
;                     const int r = r0 + rr;
;                     const u32x4 gb = gb_n, gu = gu_n; const f32x4 pv4 = pv_n;
;                     if (rr < 15) { gb_n = *(const u32x4*)(Z + (size_t)(r + 1) * INP + 768 + c0); gu_n = *(const u32x4*)(Z + (size_t)(r + 1) * INP + 1280 + c0);
;                                    pv_n = *(const f32x4*)(pl + (size_t)(r + 1) * PLE + lane * 4); }
;                     float cv[8], uu[8]; float ss = 0.f;
; #pragma unroll
;                     for (int i = 0; i < 4; ++i) {
;                         uu[2 * i] = bf_lo(gu[i]); uu[2 * i + 1] = bf_hi(gu[i]);
;                         cv[2 * i] = bf_lo(gb[i]) * (w0[2 * i] * uu[2 * i] + w1[2 * i] * u1[2 * i] + w2[2 * i] * u2[2 * i]);
;                         cv[2 * i + 1] = bf_hi(gb[i]) * (w0[2 * i + 1] * uu[2 * i + 1] + w1[2 * i + 1] * u1[2 * i + 1] + w2[2 * i + 1] * u2[2 * i + 1]);
;                     }
; #pragma unroll
;                     for (int i = 0; i < 8; ++i) { ss += cv[i] * cv[i]; u2[i] = u1[i]; u1[i] = uu[i]; }
;                     ss = wave_sum(ss);
;                     const float rc = rsqrtf(ss * (1.0f / 512.0f) + EPS);
;                     u32x4 oc;
; #pragma unroll
;                     for (int i = 0; i < 4; ++i) oc[i] = cvt_pk_bf16(cv[2 * i] * rc, cv[2 * i + 1] * rc);
;                     *(u32x4*)(MIX + (size_t)r * 1024 + 512 + c0) = oc;
	v_lshlrev_b32_e32 v196, 16, v22
	v_and_b32_e32 v197, 0xffff0000, v22
	v_lshlrev_b32_e32 v198, 16, v23
	v_and_b32_e32 v199, 0xffff0000, v23
	v_lshlrev_b32_e32 v200, 16, v24
	v_and_b32_e32 v201, 0xffff0000, v24
	v_lshlrev_b32_e32 v202, 16, v25
	v_and_b32_e32 v203, 0xffff0000, v25
	v_mul_f32_e32 v140, v164, v196
	v_mul_f32_e32 v141, v165, v197
	v_mul_f32_e32 v142, v166, v198
	v_mul_f32_e32 v143, v167, v199
	v_mul_f32_e32 v144, v168, v200
	v_mul_f32_e32 v145, v169, v201
	v_mul_f32_e32 v146, v170, v202
	v_mul_f32_e32 v147, v171, v203
	v_fmac_f32_e32 v140, v172, v188
	v_fmac_f32_e32 v141, v173, v189
	v_fmac_f32_e32 v142, v174, v190
	v_fmac_f32_e32 v143, v175, v191
	v_fmac_f32_e32 v144, v176, v192
	v_fmac_f32_e32 v145, v177, v193
	v_fmac_f32_e32 v146, v178, v194
	v_fmac_f32_e32 v147, v179, v195
	v_fmac_f32_e32 v140, v180, v204
	v_fmac_f32_e32 v141, v181, v205
	v_fmac_f32_e32 v142, v182, v206
	v_fmac_f32_e32 v143, v183, v207
	v_fmac_f32_e32 v144, v184, v208
	v_fmac_f32_e32 v145, v185, v209
	v_fmac_f32_e32 v146, v186, v210
	v_fmac_f32_e32 v147, v187, v211
	v_lshlrev_b32_e32 v150, 16, v6
	v_and_b32_e32 v151, 0xffff0000, v6
	v_mul_f32_e32 v140, v150, v140
	v_mul_f32_e32 v141, v151, v141
	v_lshlrev_b32_e32 v150, 16, v7
	v_and_b32_e32 v151, 0xffff0000, v7
	v_mul_f32_e32 v142, v150, v142
	v_mul_f32_e32 v143, v151, v143
	v_lshlrev_b32_e32 v150, 16, v8
	v_and_b32_e32 v151, 0xffff0000, v8
	v_mul_f32_e32 v144, v150, v144
	v_mul_f32_e32 v145, v151, v145
	v_lshlrev_b32_e32 v150, 16, v9
	v_and_b32_e32 v151, 0xffff0000, v9
	v_mul_f32_e32 v146, v150, v146
	v_mul_f32_e32 v147, v151, v147
	v_mul_f32_e32 v148, v140, v140
	v_fmac_f32_e32 v148, v141, v141
	v_fmac_f32_e32 v148, v142, v142
	v_fmac_f32_e32 v148, v143, v143
	v_fmac_f32_e32 v148, v144, v144
	v_fmac_f32_e32 v148, v145, v145
	v_fmac_f32_e32 v148, v146, v146
	v_fmac_f32_e32 v148, v147, v147
	s_nop 1
	v_add_f32_dpp v148, v148, v148 quad_perm:[1,0,3,2] row_mask:0xf bank_mask:0xf
	s_nop 1
	v_add_f32_dpp v148, v148, v148 quad_perm:[2,3,0,1] row_mask:0xf bank_mask:0xf
	s_nop 1
	v_add_f32_dpp v148, v148, v148 row_half_mirror row_mask:0xf bank_mask:0xf
	s_nop 1
	v_add_f32_dpp v148, v148, v148 row_mirror row_mask:0xf bank_mask:0xf
	s_nop 1
	v_add_f32_dpp v148, v148, v148 row_bcast:15 row_mask:0xa bank_mask:0xf
	s_nop 1
	v_add_f32_dpp v148, v148, v148 row_bcast:31 row_mask:0xc bank_mask:0xf
	s_nop 0
	v_readlane_b32 s0, v148, 63
	s_nop 1
	v_mov_b32_e32 v148, s0
	v_fmamk_f32 v148, v148, 0x3b000000, v162
	v_mul_f32_e32 v150, 0x4b800000, v148
	v_cmp_gt_f32_e32 vcc, s31, v148
	s_nop 1
	v_cndmask_b32_e32 v148, v148, v150, vcc
	v_rsq_f32_e32 v148, v148
	s_nop 0
	v_mul_f32_e32 v150, 0x45800000, v148
	v_cndmask_b32_e32 v149, v148, v150, vcc
	v_mul_f32_e32 v140, v149, v140
	v_mul_f32_e32 v141, v149, v141
	v_mul_f32_e32 v142, v149, v142
	v_mul_f32_e32 v143, v149, v143
	v_mul_f32_e32 v144, v149, v144
	v_mul_f32_e32 v145, v149, v145
	v_mul_f32_e32 v146, v149, v146
	v_mul_f32_e32 v147, v149, v147
	v_cvt_pk_bf16_f32 v140, v140, v141
	v_cvt_pk_bf16_f32 v141, v142, v143
	v_cvt_pk_bf16_f32 v142, v144, v145
	v_cvt_pk_bf16_f32 v143, v146, v147
	global_store_dwordx4 v[156:157], v[140:143], off offset:2048 sc1
	v_lshl_add_u64 v[156:157], v[156:157], 0, s[20:21]
	s_waitcnt vmcnt(5)
; __device__ __forceinline__ unsigned cvt_pk_bf16(float lo, float hi) { unsigned r; asm volatile("v_cvt_pk_bf16_f32 %0, %1, %2" : "=v"(r) : "v"(lo), "v"(hi)); return r; }
; __device__ __forceinline__ float bf_lo(unsigned w) { return __uint_as_float(w << 16); }
; __device__ __forceinline__ float bf_hi(unsigned w) { return __uint_as_float(w & 0xffff0000u); }
; __global__ void __launch_bounds__(512, 2) trunk_fwd(Args args) {
;     ...
;                 for (int rr = 0; rr < 16; ++rr) {
;                     const int r = r0 + rr;
;                     const u32x4 gb = gb_n, gu = gu_n; const f32x4 pv4 = pv_n;
;                     if (rr < 15) { gb_n = *(const u32x4*)(Z + (size_t)(r + 1) * INP + 768 + c0); gu_n = *(const u32x4*)(Z + (size_t)(r + 1) * INP + 1280 + c0);
;                                    pv_n = *(const f32x4*)(pl + (size_t)(r + 1) * PLE + lane * 4); }
;                     float cv[8], uu[8]; float ss = 0.f;
; #pragma unroll
;                     for (int i = 0; i < 4; ++i) {
;                         uu[2 * i] = bf_lo(gu[i]); uu[2 * i + 1] = bf_hi(gu[i]);
;                         cv[2 * i] = bf_lo(gb[i]) * (w0[2 * i] * uu[2 * i] + w1[2 * i] * u1[2 * i] + w2[2 * i] * u2[2 * i]);
;                         cv[2 * i + 1] = bf_hi(gb[i]) * (w0[2 * i + 1] * uu[2 * i + 1] + w1[2 * i + 1] * u1[2 * i + 1] + w2[2 * i + 1] * u2[2 * i + 1]);
;                     }
; #pragma unroll
;                     for (int i = 0; i < 8; ++i) { ss += cv[i] * cv[i]; u2[i] = u1[i]; u1[i] = uu[i]; }
;                     ss = wave_sum(ss);
;                     const float rc = rsqrtf(ss * (1.0f / 512.0f) + EPS);
;                     u32x4 oc;
; #pragma unroll
;                     for (int i = 0; i < 4; ++i) oc[i] = cvt_pk_bf16(cv[2 * i] * rc, cv[2 * i + 1] * rc);
;                     *(u32x4*)(MIX + (size_t)r * 1024 + 512 + c0) = oc;
;                     u32x2 pw; pw.x = cvt_pk_bf16(pv4[0], pv4[1]); pw.y = cvt_pk_bf16(pv4[2], pv4[3]);
;                     *(u32x2*)(PB + (size_t)r * PLE + lane * 4) = pw;
	v_lshlrev_b32_e32 v204, 16, v26
	v_and_b32_e32 v205, 0xffff0000, v26
	v_lshlrev_b32_e32 v206, 16, v27
	v_and_b32_e32 v207, 0xffff0000, v27
	v_lshlrev_b32_e32 v208, 16, v28
	v_and_b32_e32 v209, 0xffff0000, v28
	v_lshlrev_b32_e32 v210, 16, v29
	v_and_b32_e32 v211, 0xffff0000, v29
	v_mul_f32_e32 v140, v164, v204
	v_mul_f32_e32 v141, v165, v205
	v_mul_f32_e32 v142, v166, v206
	v_mul_f32_e32 v143, v167, v207
	v_mul_f32_e32 v144, v168, v208
	v_mul_f32_e32 v145, v169, v209
	v_mul_f32_e32 v146, v170, v210
	v_mul_f32_e32 v147, v171, v211
	v_fmac_f32_e32 v140, v172, v196
	v_fmac_f32_e32 v141, v173, v197
	v_fmac_f32_e32 v142, v174, v198
	v_fmac_f32_e32 v143, v175, v199
	v_fmac_f32_e32 v144, v176, v200
	v_fmac_f32_e32 v145, v177, v201
	v_fmac_f32_e32 v146, v178, v202
	v_fmac_f32_e32 v147, v179, v203
	v_fmac_f32_e32 v140, v180, v188
	v_fmac_f32_e32 v141, v181, v189
	v_fmac_f32_e32 v142, v182, v190
	v_fmac_f32_e32 v143, v183, v191
	v_fmac_f32_e32 v144, v184, v192
	v_fmac_f32_e32 v145, v185, v193
	v_fmac_f32_e32 v146, v186, v194
	v_fmac_f32_e32 v147, v187, v195
	v_lshlrev_b32_e32 v150, 16, v10
	v_and_b32_e32 v151, 0xffff0000, v10
	v_mul_f32_e32 v140, v150, v140
	v_mul_f32_e32 v141, v151, v141
	v_lshlrev_b32_e32 v150, 16, v11
	v_and_b32_e32 v151, 0xffff0000, v11
	v_mul_f32_e32 v142, v150, v142
	v_mul_f32_e32 v143, v151, v143
	v_lshlrev_b32_e32 v150, 16, v12
	v_and_b32_e32 v151, 0xffff0000, v12
	v_mul_f32_e32 v144, v150, v144
	v_mul_f32_e32 v145, v151, v145
	v_lshlrev_b32_e32 v150, 16, v13
	v_and_b32_e32 v151, 0xffff0000, v13
	v_mul_f32_e32 v146, v150, v146
	v_mul_f32_e32 v147, v151, v147
	v_mul_f32_e32 v148, v140, v140
	v_fmac_f32_e32 v148, v141, v141
	v_fmac_f32_e32 v148, v142, v142
	v_fmac_f32_e32 v148, v143, v143
	v_fmac_f32_e32 v148, v144, v144
	v_fmac_f32_e32 v148, v145, v145
	v_fmac_f32_e32 v148, v146, v146
	v_fmac_f32_e32 v148, v147, v147
	s_nop 1
	v_add_f32_dpp v148, v148, v148 quad_perm:[1,0,3,2] row_mask:0xf bank_mask:0xf
	s_nop 1
	v_add_f32_dpp v148, v148, v148 quad_perm:[2,3,0,1] row_mask:0xf bank_mask:0xf
	s_nop 1
	v_add_f32_dpp v148, v148, v148 row_half_mirror row_mask:0xf bank_mask:0xf
	s_nop 1
	v_add_f32_dpp v148, v148, v148 row_mirror row_mask:0xf bank_mask:0xf
	s_nop 1
	v_add_f32_dpp v148, v148, v148 row_bcast:15 row_mask:0xa bank_mask:0xf
	s_nop 1
	v_add_f32_dpp v148, v148, v148 row_bcast:31 row_mask:0xc bank_mask:0xf
	s_nop 0
	v_readlane_b32 s0, v148, 63
	s_nop 1
	v_mov_b32_e32 v148, s0
	v_fmamk_f32 v148, v148, 0x3b000000, v162
	v_mul_f32_e32 v150, 0x4b800000, v148
	v_cmp_gt_f32_e32 vcc, s31, v148
	s_nop 1
	v_cndmask_b32_e32 v148, v148, v150, vcc
	v_rsq_f32_e32 v148, v148
	s_nop 0
	v_mul_f32_e32 v150, 0x45800000, v148
	v_cndmask_b32_e32 v149, v148, v150, vcc
	v_mul_f32_e32 v140, v149, v140
	v_mul_f32_e32 v141, v149, v141
	v_mul_f32_e32 v142, v149, v142
	v_mul_f32_e32 v143, v149, v143
	v_mul_f32_e32 v144, v149, v144
	v_mul_f32_e32 v145, v149, v145
	v_mul_f32_e32 v146, v149, v146
	v_mul_f32_e32 v147, v149, v147
	v_cvt_pk_bf16_f32 v140, v140, v141
	v_cvt_pk_bf16_f32 v141, v142, v143
	v_cvt_pk_bf16_f32 v142, v144, v145
	v_cvt_pk_bf16_f32 v143, v146, v147
	global_store_dwordx4 v[156:157], v[140:143], off sc1
	s_waitcnt vmcnt(3)
	v_lshlrev_b32_e32 v188, 16, v18
	v_and_b32_e32 v189, 0xffff0000, v18
	v_lshlrev_b32_e32 v190, 16, v19
	v_and_b32_e32 v191, 0xffff0000, v19
	v_lshlrev_b32_e32 v192, 16, v20
	v_and_b32_e32 v193, 0xffff0000, v20
	v_lshlrev_b32_e32 v194, 16, v21
	v_and_b32_e32 v195, 0xffff0000, v21
	v_mul_f32_e32 v140, v164, v188
	v_mul_f32_e32 v141, v165, v189
	v_mul_f32_e32 v142, v166, v190
	v_mul_f32_e32 v143, v167, v191
	v_mul_f32_e32 v144, v168, v192
	v_mul_f32_e32 v145, v169, v193
	v_mul_f32_e32 v146, v170, v194
	v_mul_f32_e32 v147, v171, v195
	v_fmac_f32_e32 v140, v172, v204
	v_fmac_f32_e32 v141, v173, v205
	v_fmac_f32_e32 v142, v174, v206
	v_fmac_f32_e32 v143, v175, v207
	v_fmac_f32_e32 v144, v176, v208
	v_fmac_f32_e32 v145, v177, v209
	v_fmac_f32_e32 v146, v178, v210
	v_fmac_f32_e32 v147, v179, v211
	v_fmac_f32_e32 v140, v180, v196
	v_fmac_f32_e32 v141, v181, v197
	v_fmac_f32_e32 v142, v182, v198
	v_fmac_f32_e32 v143, v183, v199
	v_fmac_f32_e32 v144, v184, v200
	v_fmac_f32_e32 v145, v185, v201
	v_fmac_f32_e32 v146, v186, v202
	v_fmac_f32_e32 v147, v187, v203
	v_lshlrev_b32_e32 v150, 16, v2
	v_and_b32_e32 v151, 0xffff0000, v2
	v_mul_f32_e32 v140, v150, v140
	v_mul_f32_e32 v141, v151, v141
	v_lshlrev_b32_e32 v150, 16, v3
	v_and_b32_e32 v151, 0xffff0000, v3
	v_mul_f32_e32 v142, v150, v142
	v_mul_f32_e32 v143, v151, v143
	v_lshlrev_b32_e32 v150, 16, v4
	v_and_b32_e32 v151, 0xffff0000, v4
	v_mul_f32_e32 v144, v150, v144
	v_mul_f32_e32 v145, v151, v145
	v_lshlrev_b32_e32 v150, 16, v5
	v_and_b32_e32 v151, 0xffff0000, v5
	v_mul_f32_e32 v146, v150, v146
	v_mul_f32_e32 v147, v151, v147
	v_mul_f32_e32 v148, v140, v140
	v_fmac_f32_e32 v148, v141, v141
	v_fmac_f32_e32 v148, v142, v142
	v_fmac_f32_e32 v148, v143, v143
	v_fmac_f32_e32 v148, v144, v144
	v_fmac_f32_e32 v148, v145, v145
	v_fmac_f32_e32 v148, v146, v146
	v_fmac_f32_e32 v148, v147, v147
	s_nop 1
	v_add_f32_dpp v148, v148, v148 quad_perm:[1,0,3,2] row_mask:0xf bank_mask:0xf
	s_nop 1
	v_add_f32_dpp v148, v148, v148 quad_perm:[2,3,0,1] row_mask:0xf bank_mask:0xf
	s_nop 1
	v_add_f32_dpp v148, v148, v148 row_half_mirror row_mask:0xf bank_mask:0xf
	s_nop 1
	v_add_f32_dpp v148, v148, v148 row_mirror row_mask:0xf bank_mask:0xf
	s_nop 1
	v_add_f32_dpp v148, v148, v148 row_bcast:15 row_mask:0xa bank_mask:0xf
	s_nop 1
	v_add_f32_dpp v148, v148, v148 row_bcast:31 row_mask:0xc bank_mask:0xf
	s_nop 0
	v_readlane_b32 s0, v148, 63
	s_nop 1
	v_mov_b32_e32 v148, s0
	v_fmamk_f32 v148, v148, 0x3b000000, v162
	v_mul_f32_e32 v150, 0x4b800000, v148
	v_cmp_gt_f32_e32 vcc, s31, v148
	s_nop 1
	v_cndmask_b32_e32 v148, v148, v150, vcc
	v_rsq_f32_e32 v148, v148
	s_nop 0
	v_mul_f32_e32 v150, 0x45800000, v148
	v_cndmask_b32_e32 v149, v148, v150, vcc
	v_mul_f32_e32 v140, v149, v140
	v_mul_f32_e32 v141, v149, v141
	v_mul_f32_e32 v142, v149, v142
	v_mul_f32_e32 v143, v149, v143
	v_mul_f32_e32 v144, v149, v144
	v_mul_f32_e32 v145, v149, v145
	v_mul_f32_e32 v146, v149, v146
	v_mul_f32_e32 v147, v149, v147
	v_cvt_pk_bf16_f32 v140, v140, v141
	v_cvt_pk_bf16_f32 v141, v142, v143
	v_cvt_pk_bf16_f32 v142, v144, v145
	v_cvt_pk_bf16_f32 v143, v146, v147
	global_store_dwordx4 v[156:157], v[140:143], off offset:2048 sc1
	v_lshl_add_u64 v[156:157], v[156:157], 0, s[20:21]
	s_branch .LBB0_1053
